# address preparation of each K-loop load segment moved into the preceding MFMA run (fresh address registers), m0 writes re-padded
# speedup vs baseline: 1.0139x; 1.0005x over previous
.LBB0_232:
	ds_read_b128 v[158:161], v152
	ds_read_b128 v[162:165], v152 offset:1024
	ds_read_b128 v[166:169], v152 offset:2048
	ds_read_b128 v[170:173], v152 offset:3072
	s_mov_b32 m0, s47
	v_lshl_add_u64 v[206:207], v[142:143], 0, s[34:35]
	ds_read_b128 v[174:177], v153
	ds_read_b128 v[178:181], v153 offset:1024
	ds_read_b128 v[182:185], v153 offset:2048
	ds_read_b128 v[186:189], v153 offset:3072
	ds_read_b128 v[190:193], v153 offset:4096
	ds_read_b128 v[194:197], v153 offset:5120
	ds_read_b128 v[198:201], v153 offset:6144
	ds_read_b128 v[202:205], v153 offset:7168
	global_load_lds_dwordx4 v[206:207], off
	s_mov_b32 m0, s48
	v_lshl_add_u64 v[206:207], v[144:145], 0, s[34:35]
	global_load_lds_dwordx4 v[206:207], off
	s_waitcnt lgkmcnt(8)
	s_barrier
	s_waitcnt lgkmcnt(0)
	s_setprio 1
	v_mfma_f32_16x16x32_bf16 v[120:123], v[158:161], v[174:177], v[120:123]
	s_add_i32 s61, s34, 0xfffc0080
	v_mfma_f32_16x16x32_bf16 v[112:115], v[166:169], v[174:177], v[112:115]
	s_cmp_eq_u32 s19, 12
	v_mfma_f32_16x16x32_bf16 v[104:107], v[158:161], v[182:185], v[104:107]
	s_cselect_b64 s[36:37], -1, 0
	v_mfma_f32_16x16x32_bf16 v[96:99], v[166:169], v[182:185], v[96:99]
	s_and_b64 s[62:63], s[36:37], exec
	v_mfma_f32_16x16x32_bf16 v[88:91], v[158:161], v[190:193], v[88:91]
	s_cselect_b32 s61, 0, s61
	v_mfma_f32_16x16x32_bf16 v[80:83], v[166:169], v[190:193], v[80:83]
	s_and_b64 s[36:37], s[30:31], s[36:37]
	v_mfma_f32_16x16x32_bf16 v[72:75], v[158:161], v[198:201], v[72:75]
	s_and_b64 s[36:37], s[36:37], exec
	v_mfma_f32_16x16x32_bf16 v[60:63], v[166:169], v[198:201], v[60:63]
	s_cselect_b32 s63, s21, s27
	v_mfma_f32_16x16x32_bf16 v[120:123], v[162:165], v[178:181], v[120:123]
	s_cselect_b32 s62, s20, s26
	v_mfma_f32_16x16x32_bf16 v[112:115], v[170:173], v[178:181], v[112:115]
	s_cselect_b32 s37, s23, s29
	v_mfma_f32_16x16x32_bf16 v[104:107], v[162:165], v[186:189], v[104:107]
	s_cselect_b32 s36, s22, s28
	v_mfma_f32_16x16x32_bf16 v[96:99], v[170:173], v[186:189], v[96:99]
	s_add_u32 s36, s36, s61
	v_mfma_f32_16x16x32_bf16 v[88:91], v[162:165], v[194:197], v[88:91]
	s_addc_u32 s37, s37, 0
	v_mfma_f32_16x16x32_bf16 v[80:83], v[170:173], v[194:197], v[80:83]
	v_lshl_add_u64 v[218:219], s[36:37], 0, v[134:135]
	v_mfma_f32_16x16x32_bf16 v[72:75], v[162:165], v[202:205], v[72:75]
	v_lshl_add_u64 v[226:227], s[36:37], 0, v[130:131]
	v_mfma_f32_16x16x32_bf16 v[60:63], v[170:173], v[202:205], v[60:63]
	s_setprio 0
	s_barrier
	s_mov_b32 m0, s49
	ds_read_b128 v[206:209], v154
	ds_read_b128 v[210:213], v154 offset:1024
	ds_read_b128 v[214:217], v154 offset:2048
	global_load_lds_dwordx4 v[218:219], off
	s_mov_b32 m0, s50
	ds_read_b128 v[222:225], v154 offset:3072
	global_load_lds_dwordx4 v[226:227], off
	s_barrier
	s_waitcnt lgkmcnt(0)
	s_setprio 1
	v_mfma_f32_16x16x32_bf16 v[124:127], v[206:209], v[174:177], v[124:127]
	v_mfma_f32_16x16x32_bf16 v[116:119], v[214:217], v[174:177], v[116:119]
	v_mfma_f32_16x16x32_bf16 v[108:111], v[206:209], v[182:185], v[108:111]
	v_mfma_f32_16x16x32_bf16 v[100:103], v[214:217], v[182:185], v[100:103]
	v_mfma_f32_16x16x32_bf16 v[92:95], v[206:209], v[190:193], v[92:95]
	v_mfma_f32_16x16x32_bf16 v[84:87], v[214:217], v[190:193], v[84:87]
	v_mfma_f32_16x16x32_bf16 v[76:79], v[206:209], v[198:201], v[76:79]
	v_mfma_f32_16x16x32_bf16 v[64:67], v[214:217], v[198:201], v[64:67]
	v_mfma_f32_16x16x32_bf16 v[124:127], v[210:213], v[178:181], v[124:127]
	v_mfma_f32_16x16x32_bf16 v[116:119], v[222:225], v[178:181], v[116:119]
	v_mfma_f32_16x16x32_bf16 v[108:111], v[210:213], v[186:189], v[108:111]
	v_mfma_f32_16x16x32_bf16 v[100:103], v[222:225], v[186:189], v[100:103]
	s_add_u32 s62, s62, s61
	v_mfma_f32_16x16x32_bf16 v[92:95], v[210:213], v[194:197], v[92:95]
	s_addc_u32 s63, s63, 0
	v_mfma_f32_16x16x32_bf16 v[84:87], v[222:225], v[194:197], v[84:87]
	v_lshl_add_u64 v[228:229], s[62:63], 0, v[136:137]
	v_mfma_f32_16x16x32_bf16 v[76:79], v[210:213], v[202:205], v[76:79]
	v_lshl_add_u64 v[230:231], s[62:63], 0, v[132:133]
	v_mfma_f32_16x16x32_bf16 v[64:67], v[222:225], v[202:205], v[64:67]
	s_setprio 0
	s_mov_b32 m0, s25
	s_barrier
	ds_read_b128 v[174:177], v153 offset:16384
	ds_read_b128 v[178:181], v153 offset:17408
	ds_read_b128 v[182:185], v153 offset:18432
	ds_read_b128 v[186:189], v153 offset:19456
	ds_read_b128 v[190:193], v153 offset:20480
	ds_read_b128 v[194:197], v153 offset:21504
	ds_read_b128 v[198:201], v153 offset:22528
	global_load_lds_dwordx4 v[228:229], off
	s_mov_b32 m0, s41
	ds_read_b128 v[202:205], v153 offset:23552
	global_load_lds_dwordx4 v[230:231], off
	s_barrier
	s_waitcnt lgkmcnt(0)
	s_setprio 1
	v_mfma_f32_16x16x32_bf16 v[56:59], v[158:161], v[174:177], v[56:59]
	v_mfma_f32_16x16x32_bf16 v[48:51], v[166:169], v[174:177], v[48:51]
	v_mfma_f32_16x16x32_bf16 v[40:43], v[158:161], v[182:185], v[40:43]
	v_mfma_f32_16x16x32_bf16 v[32:35], v[166:169], v[182:185], v[32:35]
	v_mfma_f32_16x16x32_bf16 v[24:27], v[158:161], v[190:193], v[24:27]
	v_mfma_f32_16x16x32_bf16 v[16:19], v[166:169], v[190:193], v[16:19]
	v_mfma_f32_16x16x32_bf16 v[8:11], v[158:161], v[198:201], v[8:11]
	v_mfma_f32_16x16x32_bf16 v[0:3], v[166:169], v[198:201], v[0:3]
	v_mfma_f32_16x16x32_bf16 v[56:59], v[162:165], v[178:181], v[56:59]
	v_mfma_f32_16x16x32_bf16 v[48:51], v[170:173], v[178:181], v[48:51]
	v_mfma_f32_16x16x32_bf16 v[40:43], v[162:165], v[186:189], v[40:43]
	v_mfma_f32_16x16x32_bf16 v[32:35], v[170:173], v[186:189], v[32:35]
	s_add_u32 s64, s36, 0x40000
	v_mfma_f32_16x16x32_bf16 v[24:27], v[162:165], v[194:197], v[24:27]
	s_addc_u32 s65, s37, 0
	v_mfma_f32_16x16x32_bf16 v[16:19], v[170:173], v[194:197], v[16:19]
	v_lshl_add_u64 v[246:247], s[64:65], 0, v[134:135]
	v_mfma_f32_16x16x32_bf16 v[8:11], v[162:165], v[202:205], v[8:11]
	v_lshl_add_u64 v[248:249], s[64:65], 0, v[130:131]
	v_mfma_f32_16x16x32_bf16 v[0:3], v[170:173], v[202:205], v[0:3]
	s_setprio 0
	s_mov_b32 m0, s55
	s_barrier
	global_load_lds_dwordx4 v[246:247], off
	s_mov_b32 m0, s56
	s_nop 0
	global_load_lds_dwordx4 v[248:249], off
	s_waitcnt vmcnt(6)
	s_barrier
	s_setprio 1
	v_mfma_f32_16x16x32_bf16 v[68:71], v[206:209], v[174:177], v[68:71]
	v_mfma_f32_16x16x32_bf16 v[52:55], v[214:217], v[174:177], v[52:55]
	v_mfma_f32_16x16x32_bf16 v[44:47], v[206:209], v[182:185], v[44:47]
	v_mfma_f32_16x16x32_bf16 v[36:39], v[214:217], v[182:185], v[36:39]
	v_mfma_f32_16x16x32_bf16 v[28:31], v[206:209], v[190:193], v[28:31]
	v_mfma_f32_16x16x32_bf16 v[20:23], v[214:217], v[190:193], v[20:23]
	v_mfma_f32_16x16x32_bf16 v[12:15], v[206:209], v[198:201], v[12:15]
	v_mfma_f32_16x16x32_bf16 v[4:7], v[214:217], v[198:201], v[4:7]
	v_mfma_f32_16x16x32_bf16 v[68:71], v[210:213], v[178:181], v[68:71]
	v_mfma_f32_16x16x32_bf16 v[52:55], v[222:225], v[178:181], v[52:55]
	v_mfma_f32_16x16x32_bf16 v[44:47], v[210:213], v[186:189], v[44:47]
	v_mfma_f32_16x16x32_bf16 v[36:39], v[222:225], v[186:189], v[36:39]
	s_add_u32 s62, s62, 0x40000
	v_mfma_f32_16x16x32_bf16 v[28:31], v[210:213], v[194:197], v[28:31]
	s_addc_u32 s63, s63, 0
	v_mfma_f32_16x16x32_bf16 v[20:23], v[222:225], v[194:197], v[20:23]
	v_lshl_add_u64 v[250:251], s[62:63], 0, v[136:137]
	v_mfma_f32_16x16x32_bf16 v[12:15], v[210:213], v[202:205], v[12:15]
	v_lshl_add_u64 v[252:253], s[62:63], 0, v[132:133]
	v_mfma_f32_16x16x32_bf16 v[4:7], v[222:225], v[202:205], v[4:7]
	s_setprio 0
	s_barrier
	ds_read_b128 v[158:161], v155
	ds_read_b128 v[162:165], v155 offset:1024
	ds_read_b128 v[166:169], v155 offset:2048
	ds_read_b128 v[170:173], v155 offset:3072
	s_mov_b32 m0, s42
	ds_read_b128 v[174:177], v153 offset:32768
	ds_read_b128 v[178:181], v153 offset:33792
	ds_read_b128 v[182:185], v153 offset:34816
	ds_read_b128 v[186:189], v153 offset:35840
	ds_read_b128 v[190:193], v153 offset:36864
	ds_read_b128 v[194:197], v153 offset:37888
	ds_read_b128 v[198:201], v153 offset:38912
	global_load_lds_dwordx4 v[250:251], off
	s_mov_b32 m0, s43
	ds_read_b128 v[202:205], v153 offset:39936
	global_load_lds_dwordx4 v[252:253], off
	s_waitcnt lgkmcnt(8)
	s_barrier
	s_waitcnt lgkmcnt(0)
	s_setprio 1
	v_mfma_f32_16x16x32_bf16 v[120:123], v[158:161], v[174:177], v[120:123]
	v_mfma_f32_16x16x32_bf16 v[112:115], v[166:169], v[174:177], v[112:115]
	v_mfma_f32_16x16x32_bf16 v[104:107], v[158:161], v[182:185], v[104:107]
	v_mfma_f32_16x16x32_bf16 v[96:99], v[166:169], v[182:185], v[96:99]
	v_mfma_f32_16x16x32_bf16 v[88:91], v[158:161], v[190:193], v[88:91]
	v_mfma_f32_16x16x32_bf16 v[80:83], v[166:169], v[190:193], v[80:83]
	v_mfma_f32_16x16x32_bf16 v[72:75], v[158:161], v[198:201], v[72:75]
	v_mfma_f32_16x16x32_bf16 v[60:63], v[166:169], v[198:201], v[60:63]
	v_mfma_f32_16x16x32_bf16 v[120:123], v[162:165], v[178:181], v[120:123]
	v_mfma_f32_16x16x32_bf16 v[112:115], v[170:173], v[178:181], v[112:115]
	v_mfma_f32_16x16x32_bf16 v[104:107], v[162:165], v[186:189], v[104:107]
	v_mfma_f32_16x16x32_bf16 v[96:99], v[170:173], v[186:189], v[96:99]
	v_mfma_f32_16x16x32_bf16 v[88:91], v[162:165], v[194:197], v[88:91]
	v_mfma_f32_16x16x32_bf16 v[80:83], v[170:173], v[194:197], v[80:83]
	v_lshl_add_u64 v[246:247], v[218:219], 0, s[6:7]
	v_mfma_f32_16x16x32_bf16 v[72:75], v[162:165], v[202:205], v[72:75]
	v_lshl_add_u64 v[248:249], v[226:227], 0, s[6:7]
	v_mfma_f32_16x16x32_bf16 v[60:63], v[170:173], v[202:205], v[60:63]
	s_setprio 0
	s_barrier
	s_mov_b32 m0, s57
	ds_read_b128 v[206:209], v156
	ds_read_b128 v[210:213], v156 offset:1024
	ds_read_b128 v[214:217], v156 offset:2048
	global_load_lds_dwordx4 v[246:247], off
	s_mov_b32 m0, s58
	ds_read_b128 v[222:225], v156 offset:3072
	global_load_lds_dwordx4 v[248:249], off
	s_barrier
	s_waitcnt lgkmcnt(0)
	s_setprio 1
	v_mfma_f32_16x16x32_bf16 v[124:127], v[206:209], v[174:177], v[124:127]
	v_mfma_f32_16x16x32_bf16 v[116:119], v[214:217], v[174:177], v[116:119]
	v_mfma_f32_16x16x32_bf16 v[108:111], v[206:209], v[182:185], v[108:111]
	v_mfma_f32_16x16x32_bf16 v[100:103], v[214:217], v[182:185], v[100:103]
	v_mfma_f32_16x16x32_bf16 v[92:95], v[206:209], v[190:193], v[92:95]
	v_mfma_f32_16x16x32_bf16 v[84:87], v[214:217], v[190:193], v[84:87]
	v_mfma_f32_16x16x32_bf16 v[76:79], v[206:209], v[198:201], v[76:79]
	v_mfma_f32_16x16x32_bf16 v[64:67], v[214:217], v[198:201], v[64:67]
	v_mfma_f32_16x16x32_bf16 v[124:127], v[210:213], v[178:181], v[124:127]
	v_mfma_f32_16x16x32_bf16 v[116:119], v[222:225], v[178:181], v[116:119]
	v_mfma_f32_16x16x32_bf16 v[108:111], v[210:213], v[186:189], v[108:111]
	v_mfma_f32_16x16x32_bf16 v[100:103], v[222:225], v[186:189], v[100:103]
	v_mfma_f32_16x16x32_bf16 v[92:95], v[210:213], v[194:197], v[92:95]
	v_mfma_f32_16x16x32_bf16 v[84:87], v[222:225], v[194:197], v[84:87]
	v_lshl_add_u64 v[250:251], v[228:229], 0, s[6:7]
	v_mfma_f32_16x16x32_bf16 v[76:79], v[210:213], v[202:205], v[76:79]
	v_lshl_add_u64 v[252:253], v[230:231], 0, s[6:7]
	v_mfma_f32_16x16x32_bf16 v[64:67], v[222:225], v[202:205], v[64:67]
	s_setprio 0
	s_mov_b32 m0, s44
	s_barrier
	ds_read_b128 v[174:177], v153 offset:49152
	ds_read_b128 v[178:181], v153 offset:50176
	ds_read_b128 v[182:185], v153 offset:51200
	ds_read_b128 v[186:189], v153 offset:52224
	ds_read_b128 v[190:193], v153 offset:53248
	ds_read_b128 v[194:197], v153 offset:54272
	ds_read_b128 v[198:201], v153 offset:55296
	global_load_lds_dwordx4 v[250:251], off
	s_mov_b32 m0, s45
	ds_read_b128 v[202:205], v153 offset:56320
	global_load_lds_dwordx4 v[252:253], off
	s_barrier
; __device__ __forceinline__ unsigned pk2(float lo, float hi) { unsigned r; asm volatile("v_cvt_pk_bf16_f32 %0, %1, %2" : "=v"(r) : "v"(lo), "v"(hi)); return r; }
; __device__ __forceinline__ unsigned pk2(float lo, float hi) { return f2bf(lo) | (f2bf(hi) << 16); }
;     ...
;         G_PAIR(0, 1);
; #pragma unroll 1
;         for (int t = 2; t < nt; t += 2) G_PAIR(t, 0);
;     __device__ __forceinline__ void epi(const f32x4 (&acc)[2][2][4][2], const Unit& u, int wr, int wc, int fr, int fq) const {
;     ...
;         const int row0 = u.pm * 256 + wr * 64 + fr, col0 = u.pn * 128 + wc * 32 + 8 * fq;
; #pragma unroll
;         for (int ai = 0; ai < 2; ++ai)
; #pragma unroll
;             for (int m = 0; m < 4; ++m) {
;                 const int row = row0 + ai * 128 + m * 16; const float rs = rs_lds[((u.pm >> 3) & 1) * 256 + (row & 255)];
;                 const float rs2 = rs * -1.4426950408889634f, rsq = rs * rs;
;                 f32x2 v[4];
; #pragma unroll
;                 for (int n = 0; n < 2; ++n)
; #pragma unroll
;                     for (int jp = 0; jp < 2; ++jp) {
;                         const f32x2 gg = (f32x2){acc[ai][0][m][n][2 * jp], acc[ai][0][m][n][2 * jp + 1]}, uu = (f32x2){acc[ai][1][m][n][2 * jp], acc[ai][1][m][n][2 * jp + 1]};
;                         const f32x2 t = gg * rs2; f32x2 e; e.x = __builtin_amdgcn_exp2f(t.x); e.y = __builtin_amdgcn_exp2f(t.y);
;                         const f32x2 d = e + 1.0f; f32x2 r; r.x = __builtin_amdgcn_rcpf(d.x); r.y = __builtin_amdgcn_rcpf(d.y);
;                         v[n * 2 + jp] = (gg * uu) * (r * rsq);
;                     }
;                 u32x4 w; w.x = pk2(v[0].x, v[0].y); w.y = pk2(v[1].x, v[1].y); w.z = pk2(v[2].x, v[2].y); w.w = pk2(v[3].x, v[3].y);
;                 *(u32x4*)(H + (size_t)row * FF + col0) = w;
	s_waitcnt lgkmcnt(0)
	s_setprio 1
	v_mfma_f32_16x16x32_bf16 v[56:59], v[158:161], v[174:177], v[56:59]
	v_mfma_f32_16x16x32_bf16 v[48:51], v[166:169], v[174:177], v[48:51]
	v_mfma_f32_16x16x32_bf16 v[40:43], v[158:161], v[182:185], v[40:43]
	v_mfma_f32_16x16x32_bf16 v[32:35], v[166:169], v[182:185], v[32:35]
	v_mfma_f32_16x16x32_bf16 v[24:27], v[158:161], v[190:193], v[24:27]
	v_mfma_f32_16x16x32_bf16 v[16:19], v[166:169], v[190:193], v[16:19]
	v_mfma_f32_16x16x32_bf16 v[8:11], v[158:161], v[198:201], v[8:11]
	v_mfma_f32_16x16x32_bf16 v[0:3], v[166:169], v[198:201], v[0:3]
	v_mfma_f32_16x16x32_bf16 v[56:59], v[162:165], v[178:181], v[56:59]
	v_mfma_f32_16x16x32_bf16 v[48:51], v[170:173], v[178:181], v[48:51]
	v_mfma_f32_16x16x32_bf16 v[40:43], v[162:165], v[186:189], v[40:43]
	v_mfma_f32_16x16x32_bf16 v[32:35], v[170:173], v[186:189], v[32:35]
	s_add_u32 s36, s36, 0x40080
	v_mfma_f32_16x16x32_bf16 v[24:27], v[162:165], v[194:197], v[24:27]
	s_addc_u32 s37, s37, 0
	v_mfma_f32_16x16x32_bf16 v[16:19], v[170:173], v[194:197], v[16:19]
	v_lshl_add_u64 v[246:247], s[36:37], 0, v[134:135]
	v_mfma_f32_16x16x32_bf16 v[8:11], v[162:165], v[202:205], v[8:11]
	v_lshl_add_u64 v[248:249], s[36:37], 0, v[130:131]
	v_mfma_f32_16x16x32_bf16 v[0:3], v[170:173], v[202:205], v[0:3]
	s_setprio 0
	s_mov_b32 m0, s59
	s_barrier
	global_load_lds_dwordx4 v[246:247], off
	s_mov_b32 m0, s17
	s_nop 0
	global_load_lds_dwordx4 v[248:249], off
	s_waitcnt vmcnt(6)
	s_barrier
	s_setprio 1
	v_mfma_f32_16x16x32_bf16 v[68:71], v[206:209], v[174:177], v[68:71]
	v_mfma_f32_16x16x32_bf16 v[52:55], v[214:217], v[174:177], v[52:55]
	v_mfma_f32_16x16x32_bf16 v[44:47], v[206:209], v[182:185], v[44:47]
	v_mfma_f32_16x16x32_bf16 v[36:39], v[214:217], v[182:185], v[36:39]
	v_mfma_f32_16x16x32_bf16 v[28:31], v[206:209], v[190:193], v[28:31]
	v_mfma_f32_16x16x32_bf16 v[20:23], v[214:217], v[190:193], v[20:23]
	v_mfma_f32_16x16x32_bf16 v[12:15], v[206:209], v[198:201], v[12:15]
	v_mfma_f32_16x16x32_bf16 v[4:7], v[214:217], v[198:201], v[4:7]
	v_mfma_f32_16x16x32_bf16 v[68:71], v[210:213], v[178:181], v[68:71]
	v_mfma_f32_16x16x32_bf16 v[52:55], v[222:225], v[178:181], v[52:55]
	v_mfma_f32_16x16x32_bf16 v[44:47], v[210:213], v[186:189], v[44:47]
	v_mfma_f32_16x16x32_bf16 v[36:39], v[222:225], v[186:189], v[36:39]
	v_mfma_f32_16x16x32_bf16 v[28:31], v[210:213], v[194:197], v[28:31]
	v_mfma_f32_16x16x32_bf16 v[20:23], v[222:225], v[194:197], v[20:23]
	v_mfma_f32_16x16x32_bf16 v[12:15], v[210:213], v[202:205], v[12:15]
	v_mfma_f32_16x16x32_bf16 v[4:7], v[222:225], v[202:205], v[4:7]
	s_setprio 0
	s_add_i32 s19, s19, 2
	s_add_u32 s34, s34, 0x100
	s_addc_u32 s35, s35, 0
	s_cmp_gt_u32 s19, 13
	s_barrier
	s_cbranch_scc0 .LBB0_232
	s_lshl_b32 s17, s24, 7
	s_and_b32 s17, s17, 0x400
	s_add_i32 s17, s17, 0
	s_add_i32 s17, s17, 0x20000
	v_lshl_add_u32 v142, v151, 2, s17
	ds_read_b32 v143, v142
	v_lshl_add_u32 v142, s24, 8, v129
	v_lshl_or_b32 v144, s60, 7, v150
	v_ashrrev_i32_e32 v145, 31, v144
	s_and_b64 vcc, exec, s[14:15]
	s_waitcnt lgkmcnt(0)
	v_mul_f32_e32 v158, 0xbfb8aa3b, v143
	v_pk_mul_f32 v[160:161], v[120:121], v[158:159] op_sel_hi:[1,0]
	v_pk_mul_f32 v[164:165], v[122:123], v[158:159] op_sel_hi:[1,0]
	v_exp_f32_e32 v160, v160
	v_exp_f32_e32 v161, v161
	v_exp_f32_e32 v164, v164
	v_exp_f32_e32 v165, v165
	v_pk_mul_f32 v[122:123], v[122:123], v[126:127]
	v_pk_add_f32 v[160:161], v[160:161], 1.0 op_sel_hi:[1,0]
	v_mul_f32_e32 v162, v143, v143
	v_rcp_f32_e32 v160, v160
	v_rcp_f32_e32 v161, v161
	v_pk_add_f32 v[126:127], v[164:165], 1.0 op_sel_hi:[1,0]
	v_pk_mul_f32 v[120:121], v[120:121], v[124:125]
	v_rcp_f32_e32 v126, v126
	v_rcp_f32_e32 v127, v127
	v_pk_mul_f32 v[124:125], v[162:163], v[160:161] op_sel_hi:[0,1]
	v_pk_mul_f32 v[160:161], v[112:113], v[158:159] op_sel_hi:[1,0]
	v_pk_mul_f32 v[120:121], v[120:121], v[124:125]
	v_exp_f32_e32 v160, v160
	v_exp_f32_e32 v161, v161
	v_pk_mul_f32 v[124:125], v[162:163], v[126:127] op_sel_hi:[0,1]
	v_pk_mul_f32 v[126:127], v[114:115], v[158:159] op_sel_hi:[1,0]
	v_pk_mul_f32 v[122:123], v[122:123], v[124:125]
	v_exp_f32_e32 v126, v126
	v_exp_f32_e32 v127, v127
	v_pk_add_f32 v[124:125], v[160:161], 1.0 op_sel_hi:[1,0]
	v_pk_mul_f32 v[114:115], v[114:115], v[118:119]
	v_rcp_f32_e32 v124, v124
	v_rcp_f32_e32 v125, v125
	v_pk_add_f32 v[118:119], v[126:127], 1.0 op_sel_hi:[1,0]
	v_pk_mul_f32 v[112:113], v[112:113], v[116:117]
	v_rcp_f32_e32 v118, v118
	v_rcp_f32_e32 v119, v119
	v_pk_mul_f32 v[116:117], v[162:163], v[124:125] op_sel_hi:[0,1]
	v_pk_mul_f32 v[112:113], v[112:113], v[116:117]
	s_mov_b32 s60, s16
	v_pk_mul_f32 v[116:117], v[162:163], v[118:119] op_sel_hi:[0,1]
	v_pk_mul_f32 v[114:115], v[114:115], v[116:117]
	v_cvt_pk_bf16_f32 v116, v120, v121
	v_cvt_pk_bf16_f32 v117, v122, v123
	v_cvt_pk_bf16_f32 v118, v112, v113
	v_bitop3_b32 v112, v142, s52, 16 bitop3:0xc8
	v_lshl_add_u32 v112, v112, 2, s17
	v_cvt_pk_bf16_f32 v119, v114, v115
	ds_read_b32 v123, v112
	v_mov_b64_e32 v[112:113], s[2:3]
	v_mad_i64_i32 v[120:121], s[26:27], v142, s51, v[112:113]
	v_lshlrev_b64 v[114:115], 1, v[144:145]
	s_waitcnt lgkmcnt(0)
; __device__ __forceinline__ unsigned pk2(float lo, float hi) { unsigned r; asm volatile("v_cvt_pk_bf16_f32 %0, %1, %2" : "=v"(r) : "v"(lo), "v"(hi)); return r; }
; __device__ __forceinline__ unsigned pk2(float lo, float hi) { return f2bf(lo) | (f2bf(hi) << 16); }
;     __device__ __forceinline__ void epi(const f32x4 (&acc)[2][2][4][2], const Unit& u, int wr, int wc, int fr, int fq) const {
;     ...
;         for (int ai = 0; ai < 2; ++ai)
; #pragma unroll
;             for (int m = 0; m < 4; ++m) {
;                 const int row = row0 + ai * 128 + m * 16; const float rs = rs_lds[((u.pm >> 3) & 1) * 256 + (row & 255)];
;                 const float rs2 = rs * -1.4426950408889634f, rsq = rs * rs;
;                 f32x2 v[4];
; #pragma unroll
;                 for (int n = 0; n < 2; ++n)
; #pragma unroll
;                     for (int jp = 0; jp < 2; ++jp) {
;                         const f32x2 gg = (f32x2){acc[ai][0][m][n][2 * jp], acc[ai][0][m][n][2 * jp + 1]}, uu = (f32x2){acc[ai][1][m][n][2 * jp], acc[ai][1][m][n][2 * jp + 1]};
;                         const f32x2 t = gg * rs2; f32x2 e; e.x = __builtin_amdgcn_exp2f(t.x); e.y = __builtin_amdgcn_exp2f(t.y);
;                         const f32x2 d = e + 1.0f; f32x2 r; r.x = __builtin_amdgcn_rcpf(d.x); r.y = __builtin_amdgcn_rcpf(d.y);
;                         v[n * 2 + jp] = (gg * uu) * (r * rsq);
;                     }
;                 u32x4 w; w.x = pk2(v[0].x, v[0].y); w.y = pk2(v[1].x, v[1].y); w.z = pk2(v[2].x, v[2].y); w.w = pk2(v[3].x, v[3].y);
;                 *(u32x4*)(H + (size_t)row * FF + col0) = w;
	v_mul_f32_e32 v122, 0xbfb8aa3b, v123
	v_pk_mul_f32 v[124:125], v[104:105], v[122:123] op_sel_hi:[1,0]
	v_lshl_add_u64 v[120:121], v[120:121], 0, v[114:115]
	v_exp_f32_e32 v124, v124
	v_exp_f32_e32 v125, v125
	global_store_dwordx4 v[120:121], v[116:119], off
	v_pk_mul_f32 v[120:121], v[106:107], v[122:123] op_sel_hi:[1,0]
	v_pk_mul_f32 v[106:107], v[106:107], v[110:111]
	v_exp_f32_e32 v120, v120
	v_exp_f32_e32 v121, v121
	v_pk_add_f32 v[118:119], v[124:125], 1.0 op_sel_hi:[1,0]
	v_mul_f32_e32 v116, v123, v123
	v_rcp_f32_e32 v118, v118
	v_rcp_f32_e32 v119, v119
	v_pk_add_f32 v[110:111], v[120:121], 1.0 op_sel_hi:[1,0]
	v_pk_mul_f32 v[104:105], v[104:105], v[108:109]
	v_rcp_f32_e32 v110, v110
	v_rcp_f32_e32 v111, v111
	v_pk_mul_f32 v[108:109], v[116:117], v[118:119] op_sel_hi:[0,1]
	v_pk_mul_f32 v[118:119], v[96:97], v[122:123] op_sel_hi:[1,0]
	v_pk_mul_f32 v[104:105], v[104:105], v[108:109]
	v_exp_f32_e32 v118, v118
	v_exp_f32_e32 v119, v119
	v_pk_mul_f32 v[108:109], v[116:117], v[110:111] op_sel_hi:[0,1]
	v_pk_mul_f32 v[110:111], v[98:99], v[122:123] op_sel_hi:[1,0]
	v_pk_mul_f32 v[106:107], v[106:107], v[108:109]
	v_exp_f32_e32 v110, v110
	v_exp_f32_e32 v111, v111
	v_pk_add_f32 v[108:109], v[118:119], 1.0 op_sel_hi:[1,0]
	v_pk_mul_f32 v[98:99], v[98:99], v[102:103]
	v_rcp_f32_e32 v108, v108
	v_rcp_f32_e32 v109, v109
	v_pk_add_f32 v[102:103], v[110:111], 1.0 op_sel_hi:[1,0]
	v_pk_mul_f32 v[96:97], v[96:97], v[100:101]
	v_rcp_f32_e32 v102, v102
	v_rcp_f32_e32 v103, v103
	v_pk_mul_f32 v[100:101], v[116:117], v[108:109] op_sel_hi:[0,1]
	v_pk_mul_f32 v[100:101], v[96:97], v[100:101]
	s_mov_b32 s24, s18
	v_pk_mul_f32 v[96:97], v[116:117], v[102:103] op_sel_hi:[0,1]
	v_pk_mul_f32 v[102:103], v[98:99], v[96:97]
	v_cvt_pk_bf16_f32 v96, v104, v105
	v_cvt_pk_bf16_f32 v97, v106, v107
	v_cvt_pk_bf16_f32 v98, v100, v101
	v_bitop3_b32 v100, v142, s53, 32 bitop3:0xc8
	v_lshl_add_u32 v100, v100, 2, s17
	v_cvt_pk_bf16_f32 v99, v102, v103
	ds_read_b32 v103, v100
	v_or_b32_e32 v100, 16, v142
	v_mad_i64_i32 v[100:101], s[26:27], v100, s51, v[112:113]
	v_lshl_add_u64 v[100:101], v[100:101], 0, v[114:115]
	s_waitcnt lgkmcnt(0)
	v_mul_f32_e32 v102, 0xbfb8aa3b, v103
	v_pk_mul_f32 v[104:105], v[88:89], v[102:103] op_sel_hi:[1,0]
	global_store_dwordx4 v[100:101], v[96:99], off
	v_exp_f32_e32 v104, v104
	v_exp_f32_e32 v105, v105
	v_pk_mul_f32 v[100:101], v[90:91], v[102:103] op_sel_hi:[1,0]
	v_pk_mul_f32 v[90:91], v[90:91], v[94:95]
	v_exp_f32_e32 v100, v100
	v_exp_f32_e32 v101, v101
	v_pk_add_f32 v[98:99], v[104:105], 1.0 op_sel_hi:[1,0]
	v_mul_f32_e32 v96, v103, v103
	v_rcp_f32_e32 v98, v98
	v_rcp_f32_e32 v99, v99
	v_pk_add_f32 v[94:95], v[100:101], 1.0 op_sel_hi:[1,0]
	v_pk_mul_f32 v[88:89], v[88:89], v[92:93]
	v_rcp_f32_e32 v94, v94
	v_rcp_f32_e32 v95, v95
	v_pk_mul_f32 v[92:93], v[96:97], v[98:99] op_sel_hi:[0,1]
	v_pk_mul_f32 v[98:99], v[80:81], v[102:103] op_sel_hi:[1,0]
	v_pk_mul_f32 v[88:89], v[88:89], v[92:93]
	v_exp_f32_e32 v98, v98
	v_exp_f32_e32 v99, v99
	v_pk_mul_f32 v[92:93], v[96:97], v[94:95] op_sel_hi:[0,1]
	v_pk_mul_f32 v[94:95], v[82:83], v[102:103] op_sel_hi:[1,0]
	v_pk_mul_f32 v[90:91], v[90:91], v[92:93]
	v_exp_f32_e32 v94, v94
	v_exp_f32_e32 v95, v95
	v_pk_add_f32 v[92:93], v[98:99], 1.0 op_sel_hi:[1,0]
	v_pk_mul_f32 v[82:83], v[82:83], v[86:87]
	v_rcp_f32_e32 v92, v92
	v_rcp_f32_e32 v93, v93
	v_pk_add_f32 v[86:87], v[94:95], 1.0 op_sel_hi:[1,0]
	v_pk_mul_f32 v[80:81], v[80:81], v[84:85]
	v_rcp_f32_e32 v86, v86
	v_rcp_f32_e32 v87, v87
	v_pk_mul_f32 v[84:85], v[96:97], v[92:93] op_sel_hi:[0,1]
	v_pk_mul_f32 v[84:85], v[80:81], v[84:85]
	s_mov_b64 s[28:29], s[22:23]
	v_pk_mul_f32 v[80:81], v[96:97], v[86:87] op_sel_hi:[0,1]
	v_pk_mul_f32 v[86:87], v[82:83], v[80:81]
	v_cvt_pk_bf16_f32 v80, v88, v89
	v_cvt_pk_bf16_f32 v81, v90, v91
	v_cvt_pk_bf16_f32 v82, v84, v85
	v_bitop3_b32 v84, v142, s54, 48 bitop3:0xc8
	v_lshl_add_u32 v84, v84, 2, s17
	v_cvt_pk_bf16_f32 v83, v86, v87
	ds_read_b32 v87, v84
	v_or_b32_e32 v84, 32, v142
	v_mad_i64_i32 v[84:85], s[26:27], v84, s51, v[112:113]
	v_lshl_add_u64 v[84:85], v[84:85], 0, v[114:115]
	s_waitcnt lgkmcnt(0)
	v_mul_f32_e32 v86, 0xbfb8aa3b, v87
	v_pk_mul_f32 v[88:89], v[72:73], v[86:87] op_sel_hi:[1,0]
	global_store_dwordx4 v[84:85], v[80:83], off
	v_exp_f32_e32 v88, v88
	v_exp_f32_e32 v89, v89
	v_pk_mul_f32 v[84:85], v[74:75], v[86:87] op_sel_hi:[1,0]
	v_pk_mul_f32 v[74:75], v[74:75], v[78:79]
	v_exp_f32_e32 v84, v84
	v_exp_f32_e32 v85, v85
	v_pk_add_f32 v[82:83], v[88:89], 1.0 op_sel_hi:[1,0]
	v_mul_f32_e32 v80, v87, v87
	v_rcp_f32_e32 v82, v82
	v_rcp_f32_e32 v83, v83
	v_pk_add_f32 v[78:79], v[84:85], 1.0 op_sel_hi:[1,0]
	v_pk_mul_f32 v[72:73], v[72:73], v[76:77]
	v_rcp_f32_e32 v78, v78
	v_rcp_f32_e32 v79, v79
	v_pk_mul_f32 v[76:77], v[80:81], v[82:83] op_sel_hi:[0,1]
	v_pk_mul_f32 v[82:83], v[60:61], v[86:87] op_sel_hi:[1,0]
	v_pk_mul_f32 v[72:73], v[72:73], v[76:77]
	v_exp_f32_e32 v82, v82
	v_exp_f32_e32 v83, v83
	v_pk_mul_f32 v[76:77], v[80:81], v[78:79] op_sel_hi:[0,1]
	v_pk_mul_f32 v[78:79], v[62:63], v[86:87] op_sel_hi:[1,0]
	v_pk_mul_f32 v[74:75], v[74:75], v[76:77]
	v_exp_f32_e32 v78, v78
	v_exp_f32_e32 v79, v79
	v_pk_add_f32 v[76:77], v[82:83], 1.0 op_sel_hi:[1,0]
	v_pk_mul_f32 v[62:63], v[62:63], v[66:67]
	v_rcp_f32_e32 v76, v76
	v_rcp_f32_e32 v77, v77
	v_pk_add_f32 v[66:67], v[78:79], 1.0 op_sel_hi:[1,0]
	v_pk_mul_f32 v[60:61], v[60:61], v[64:65]
	v_rcp_f32_e32 v66, v66
	v_rcp_f32_e32 v67, v67
	v_pk_mul_f32 v[64:65], v[80:81], v[76:77] op_sel_hi:[0,1]
	v_pk_mul_f32 v[64:65], v[60:61], v[64:65]
	v_pk_mul_f32 v[60:61], v[80:81], v[66:67] op_sel_hi:[0,1]
	v_pk_mul_f32 v[66:67], v[62:63], v[60:61]
	v_cvt_pk_bf16_f32 v60, v72, v73
	v_cvt_pk_bf16_f32 v61, v74, v75
	v_cvt_pk_bf16_f32 v62, v64, v65
	s_nop 0
	v_cvt_pk_bf16_f32 v63, v66, v67
	v_add_u32_e32 v67, 0x80, v142
	v_and_b32_e32 v64, 0xcf, v67
	v_lshl_add_u32 v64, v64, 2, s17
	ds_read_b32 v74, v64
	v_or_b32_e32 v64, 48, v142
	v_mad_i64_i32 v[64:65], s[26:27], v64, s51, v[112:113]
	v_lshl_add_u64 v[64:65], v[64:65], 0, v[114:115]
	s_waitcnt lgkmcnt(0)
; __device__ __forceinline__ unsigned pk2(float lo, float hi) { unsigned r; asm volatile("v_cvt_pk_bf16_f32 %0, %1, %2" : "=v"(r) : "v"(lo), "v"(hi)); return r; }
; __device__ __forceinline__ unsigned pk2(float lo, float hi) { return f2bf(lo) | (f2bf(hi) << 16); }
;     __device__ __forceinline__ void epi(const f32x4 (&acc)[2][2][4][2], const Unit& u, int wr, int wc, int fr, int fq) const {
;     ...
;         for (int ai = 0; ai < 2; ++ai)
; #pragma unroll
;             for (int m = 0; m < 4; ++m) {
;                 const int row = row0 + ai * 128 + m * 16; const float rs = rs_lds[((u.pm >> 3) & 1) * 256 + (row & 255)];
;                 const float rs2 = rs * -1.4426950408889634f, rsq = rs * rs;
;                 f32x2 v[4];
; #pragma unroll
;                 for (int n = 0; n < 2; ++n)
; #pragma unroll
;                     for (int jp = 0; jp < 2; ++jp) {
;                         const f32x2 gg = (f32x2){acc[ai][0][m][n][2 * jp], acc[ai][0][m][n][2 * jp + 1]}, uu = (f32x2){acc[ai][1][m][n][2 * jp], acc[ai][1][m][n][2 * jp + 1]};
;                         const f32x2 t = gg * rs2; f32x2 e; e.x = __builtin_amdgcn_exp2f(t.x); e.y = __builtin_amdgcn_exp2f(t.y);
;                         const f32x2 d = e + 1.0f; f32x2 r; r.x = __builtin_amdgcn_rcpf(d.x); r.y = __builtin_amdgcn_rcpf(d.y);
;                         v[n * 2 + jp] = (gg * uu) * (r * rsq);
;                     }
;                 u32x4 w; w.x = pk2(v[0].x, v[0].y); w.y = pk2(v[1].x, v[1].y); w.z = pk2(v[2].x, v[2].y); w.w = pk2(v[3].x, v[3].y);
;                 *(u32x4*)(H + (size_t)row * FF + col0) = w;
	v_mul_f32_e32 v66, 0xbfb8aa3b, v74
	v_pk_mul_f32 v[72:73], v[56:57], v[66:67] op_sel_hi:[1,0]
	global_store_dwordx4 v[64:65], v[60:63], off
	v_exp_f32_e32 v72, v72
	v_exp_f32_e32 v73, v73
	v_pk_mul_f32 v[64:65], v[58:59], v[66:67] op_sel_hi:[1,0]
	v_mul_f32_e32 v60, v74, v74
	v_exp_f32_e32 v64, v64
	v_exp_f32_e32 v65, v65
	v_pk_add_f32 v[62:63], v[72:73], 1.0 op_sel_hi:[1,0]
	v_pk_mul_f32 v[56:57], v[56:57], v[68:69]
	v_rcp_f32_e32 v62, v62
	v_rcp_f32_e32 v63, v63
	v_pk_add_f32 v[64:65], v[64:65], 1.0 op_sel_hi:[1,0]
	v_pk_mul_f32 v[68:69], v[48:49], v[66:67] op_sel_hi:[1,0]
	v_rcp_f32_e32 v64, v64
	v_rcp_f32_e32 v65, v65
	v_pk_mul_f32 v[62:63], v[60:61], v[62:63] op_sel_hi:[0,1]
	v_exp_f32_e32 v68, v68
	v_exp_f32_e32 v69, v69
	v_pk_mul_f32 v[56:57], v[56:57], v[62:63]
	v_pk_mul_f32 v[62:63], v[60:61], v[64:65] op_sel_hi:[0,1]
	v_pk_mul_f32 v[64:65], v[50:51], v[66:67] op_sel_hi:[1,0]
	v_pk_mul_f32 v[58:59], v[58:59], v[70:71]
	v_exp_f32_e32 v64, v64
	v_exp_f32_e32 v65, v65
	v_pk_mul_f32 v[58:59], v[58:59], v[62:63]
	v_pk_add_f32 v[62:63], v[68:69], 1.0 op_sel_hi:[1,0]
	v_pk_mul_f32 v[50:51], v[50:51], v[54:55]
	v_rcp_f32_e32 v62, v62
	v_rcp_f32_e32 v63, v63
	v_pk_add_f32 v[54:55], v[64:65], 1.0 op_sel_hi:[1,0]
	v_pk_mul_f32 v[48:49], v[48:49], v[52:53]
	v_rcp_f32_e32 v54, v54
	v_rcp_f32_e32 v55, v55
	v_pk_mul_f32 v[52:53], v[60:61], v[62:63] op_sel_hi:[0,1]
	v_pk_mul_f32 v[52:53], v[48:49], v[52:53]
	v_pk_mul_f32 v[48:49], v[60:61], v[54:55] op_sel_hi:[0,1]
	v_pk_mul_f32 v[54:55], v[50:51], v[48:49]
	v_cvt_pk_bf16_f32 v48, v56, v57
	v_cvt_pk_bf16_f32 v49, v58, v59
	v_cvt_pk_bf16_f32 v50, v52, v53
	s_nop 0
	v_cvt_pk_bf16_f32 v51, v54, v55
	v_add_u32_e32 v55, 0x90, v142
	v_and_b32_e32 v52, 0xdf, v55
	v_lshl_add_u32 v52, v52, 2, s17
	ds_read_b32 v58, v52
	v_mad_i64_i32 v[52:53], s[26:27], v67, s51, v[112:113]
	v_lshl_add_u64 v[52:53], v[52:53], 0, v[114:115]
	global_store_dwordx4 v[52:53], v[48:51], off
	s_waitcnt lgkmcnt(0)
	v_mul_f32_e32 v54, 0xbfb8aa3b, v58
	v_pk_mul_f32 v[56:57], v[40:41], v[54:55] op_sel_hi:[1,0]
	v_pk_mul_f32 v[52:53], v[42:43], v[54:55] op_sel_hi:[1,0]
	v_exp_f32_e32 v56, v56
	v_exp_f32_e32 v57, v57
	v_exp_f32_e32 v52, v52
	v_exp_f32_e32 v53, v53
	v_pk_mul_f32 v[42:43], v[42:43], v[46:47]
	v_pk_add_f32 v[50:51], v[56:57], 1.0 op_sel_hi:[1,0]
	v_mul_f32_e32 v48, v58, v58
	v_rcp_f32_e32 v50, v50
	v_rcp_f32_e32 v51, v51
	v_pk_add_f32 v[46:47], v[52:53], 1.0 op_sel_hi:[1,0]
	v_pk_mul_f32 v[40:41], v[40:41], v[44:45]
	v_rcp_f32_e32 v46, v46
	v_rcp_f32_e32 v47, v47
	v_pk_mul_f32 v[44:45], v[48:49], v[50:51] op_sel_hi:[0,1]
	v_pk_mul_f32 v[50:51], v[32:33], v[54:55] op_sel_hi:[1,0]
	v_pk_mul_f32 v[40:41], v[40:41], v[44:45]
	v_exp_f32_e32 v50, v50
	v_exp_f32_e32 v51, v51
	v_pk_mul_f32 v[44:45], v[48:49], v[46:47] op_sel_hi:[0,1]
	v_pk_mul_f32 v[46:47], v[34:35], v[54:55] op_sel_hi:[1,0]
	v_pk_mul_f32 v[42:43], v[42:43], v[44:45]
	v_exp_f32_e32 v46, v46
	v_exp_f32_e32 v47, v47
	v_pk_add_f32 v[44:45], v[50:51], 1.0 op_sel_hi:[1,0]
	v_pk_mul_f32 v[34:35], v[34:35], v[38:39]
	v_rcp_f32_e32 v44, v44
	v_rcp_f32_e32 v45, v45
	v_pk_add_f32 v[38:39], v[46:47], 1.0 op_sel_hi:[1,0]
	v_pk_mul_f32 v[32:33], v[32:33], v[36:37]
	v_rcp_f32_e32 v38, v38
	v_rcp_f32_e32 v39, v39
	v_pk_mul_f32 v[36:37], v[48:49], v[44:45] op_sel_hi:[0,1]
	v_pk_mul_f32 v[36:37], v[32:33], v[36:37]
	v_pk_mul_f32 v[32:33], v[48:49], v[38:39] op_sel_hi:[0,1]
	v_pk_mul_f32 v[38:39], v[34:35], v[32:33]
	v_cvt_pk_bf16_f32 v32, v40, v41
	v_cvt_pk_bf16_f32 v33, v42, v43
	v_cvt_pk_bf16_f32 v34, v36, v37
	s_nop 0
	v_cvt_pk_bf16_f32 v35, v38, v39
	v_add_u32_e32 v39, 0xa0, v142
	v_and_b32_e32 v36, 0xef, v39
	v_lshl_add_u32 v36, v36, 2, s17
	ds_read_b32 v42, v36
	v_mad_i64_i32 v[36:37], s[26:27], v55, s51, v[112:113]
	v_lshl_add_u64 v[36:37], v[36:37], 0, v[114:115]
	global_store_dwordx4 v[36:37], v[32:35], off
	s_waitcnt lgkmcnt(0)
; __device__ __forceinline__ unsigned pk2(float lo, float hi) { unsigned r; asm volatile("v_cvt_pk_bf16_f32 %0, %1, %2" : "=v"(r) : "v"(lo), "v"(hi)); return r; }
; __device__ __forceinline__ unsigned pk2(float lo, float hi) { return f2bf(lo) | (f2bf(hi) << 16); }
; #define G_WAIT_V(n) asm volatile("s_waitcnt vmcnt(" #n ")" ::: "memory")
; #define G_BAR __builtin_amdgcn_s_barrier()
;     ...
;         if (!has_next) break;
;         cur = nxt; cA = nA; cB = nB; cA2 = nA2; cB2 = nB2; ++ui;
;     }
;     G_WAIT_V(0);
;     if (wr == 0) G_BAR;
;     __device__ __forceinline__ void epi(const f32x4 (&acc)[2][2][4][2], const Unit& u, int wr, int wc, int fr, int fq) const {
;     ...
;         for (int ai = 0; ai < 2; ++ai)
; #pragma unroll
;             for (int m = 0; m < 4; ++m) {
;                 const int row = row0 + ai * 128 + m * 16; const float rs = rs_lds[((u.pm >> 3) & 1) * 256 + (row & 255)];
;                 const float rs2 = rs * -1.4426950408889634f, rsq = rs * rs;
;                 f32x2 v[4];
; #pragma unroll
;                 for (int n = 0; n < 2; ++n)
; #pragma unroll
;                     for (int jp = 0; jp < 2; ++jp) {
;                         const f32x2 gg = (f32x2){acc[ai][0][m][n][2 * jp], acc[ai][0][m][n][2 * jp + 1]}, uu = (f32x2){acc[ai][1][m][n][2 * jp], acc[ai][1][m][n][2 * jp + 1]};
;                         const f32x2 t = gg * rs2; f32x2 e; e.x = __builtin_amdgcn_exp2f(t.x); e.y = __builtin_amdgcn_exp2f(t.y);
;                         const f32x2 d = e + 1.0f; f32x2 r; r.x = __builtin_amdgcn_rcpf(d.x); r.y = __builtin_amdgcn_rcpf(d.y);
;                         v[n * 2 + jp] = (gg * uu) * (r * rsq);
;                     }
;                 u32x4 w; w.x = pk2(v[0].x, v[0].y); w.y = pk2(v[1].x, v[1].y); w.z = pk2(v[2].x, v[2].y); w.w = pk2(v[3].x, v[3].y);
;                 *(u32x4*)(H + (size_t)row * FF + col0) = w;
	v_mul_f32_e32 v38, 0xbfb8aa3b, v42
	v_pk_mul_f32 v[40:41], v[24:25], v[38:39] op_sel_hi:[1,0]
	v_pk_mul_f32 v[36:37], v[26:27], v[38:39] op_sel_hi:[1,0]
	v_exp_f32_e32 v40, v40
	v_exp_f32_e32 v41, v41
	v_exp_f32_e32 v36, v36
	v_exp_f32_e32 v37, v37
	v_pk_mul_f32 v[26:27], v[26:27], v[30:31]
	v_pk_add_f32 v[34:35], v[40:41], 1.0 op_sel_hi:[1,0]
	v_mul_f32_e32 v32, v42, v42
	v_rcp_f32_e32 v34, v34
	v_rcp_f32_e32 v35, v35
	v_pk_add_f32 v[30:31], v[36:37], 1.0 op_sel_hi:[1,0]
	v_pk_mul_f32 v[24:25], v[24:25], v[28:29]
	v_rcp_f32_e32 v30, v30
	v_rcp_f32_e32 v31, v31
	v_pk_mul_f32 v[28:29], v[32:33], v[34:35] op_sel_hi:[0,1]
	v_pk_mul_f32 v[34:35], v[16:17], v[38:39] op_sel_hi:[1,0]
	v_pk_mul_f32 v[24:25], v[24:25], v[28:29]
	v_exp_f32_e32 v34, v34
	v_exp_f32_e32 v35, v35
	v_pk_mul_f32 v[28:29], v[32:33], v[30:31] op_sel_hi:[0,1]
	v_pk_mul_f32 v[30:31], v[18:19], v[38:39] op_sel_hi:[1,0]
	v_pk_mul_f32 v[26:27], v[26:27], v[28:29]
	v_exp_f32_e32 v30, v30
	v_exp_f32_e32 v31, v31
	v_pk_add_f32 v[28:29], v[34:35], 1.0 op_sel_hi:[1,0]
	v_pk_mul_f32 v[18:19], v[18:19], v[22:23]
	v_rcp_f32_e32 v28, v28
	v_rcp_f32_e32 v29, v29
	v_pk_add_f32 v[22:23], v[30:31], 1.0 op_sel_hi:[1,0]
	v_pk_mul_f32 v[16:17], v[16:17], v[20:21]
	v_rcp_f32_e32 v22, v22
	v_rcp_f32_e32 v23, v23
	v_pk_mul_f32 v[20:21], v[32:33], v[28:29] op_sel_hi:[0,1]
	v_pk_mul_f32 v[20:21], v[16:17], v[20:21]
	v_pk_mul_f32 v[16:17], v[32:33], v[22:23] op_sel_hi:[0,1]
	v_pk_mul_f32 v[22:23], v[18:19], v[16:17]
	v_cvt_pk_bf16_f32 v16, v24, v25
	v_cvt_pk_bf16_f32 v17, v26, v27
	v_cvt_pk_bf16_f32 v18, v20, v21
	s_nop 0
	v_cvt_pk_bf16_f32 v19, v22, v23
	v_add_u32_e32 v23, 0xb0, v142
	v_and_b32_e32 v20, 0xff, v23
	v_lshl_add_u32 v20, v20, 2, s17
	ds_read_b32 v26, v20
	v_mad_i64_i32 v[20:21], s[26:27], v39, s51, v[112:113]
	v_lshl_add_u64 v[20:21], v[20:21], 0, v[114:115]
	global_store_dwordx4 v[20:21], v[16:19], off
	s_waitcnt lgkmcnt(0)
	v_mul_f32_e32 v22, 0xbfb8aa3b, v26
	v_pk_mul_f32 v[24:25], v[8:9], v[22:23] op_sel_hi:[1,0]
	v_pk_mul_f32 v[20:21], v[10:11], v[22:23] op_sel_hi:[1,0]
	v_exp_f32_e32 v24, v24
	v_exp_f32_e32 v25, v25
	v_exp_f32_e32 v20, v20
	v_exp_f32_e32 v21, v21
	v_pk_mul_f32 v[10:11], v[10:11], v[14:15]
	v_pk_add_f32 v[18:19], v[24:25], 1.0 op_sel_hi:[1,0]
	v_mul_f32_e32 v16, v26, v26
	v_rcp_f32_e32 v18, v18
	v_rcp_f32_e32 v19, v19
	v_pk_add_f32 v[14:15], v[20:21], 1.0 op_sel_hi:[1,0]
	v_pk_mul_f32 v[8:9], v[8:9], v[12:13]
	v_rcp_f32_e32 v14, v14
	v_rcp_f32_e32 v15, v15
	v_pk_mul_f32 v[12:13], v[16:17], v[18:19] op_sel_hi:[0,1]
	v_pk_mul_f32 v[18:19], v[0:1], v[22:23] op_sel_hi:[1,0]
	v_pk_mul_f32 v[8:9], v[8:9], v[12:13]
	v_exp_f32_e32 v18, v18
	v_exp_f32_e32 v19, v19
	v_pk_mul_f32 v[12:13], v[16:17], v[14:15] op_sel_hi:[0,1]
	v_pk_mul_f32 v[14:15], v[2:3], v[22:23] op_sel_hi:[1,0]
	v_pk_mul_f32 v[10:11], v[10:11], v[12:13]
	v_exp_f32_e32 v14, v14
	v_exp_f32_e32 v15, v15
	v_pk_add_f32 v[12:13], v[18:19], 1.0 op_sel_hi:[1,0]
	v_pk_mul_f32 v[2:3], v[2:3], v[6:7]
	v_rcp_f32_e32 v12, v12
	v_rcp_f32_e32 v13, v13
	v_pk_add_f32 v[6:7], v[14:15], 1.0 op_sel_hi:[1,0]
	v_pk_mul_f32 v[0:1], v[0:1], v[4:5]
	v_rcp_f32_e32 v6, v6
	v_rcp_f32_e32 v7, v7
	v_pk_mul_f32 v[4:5], v[16:17], v[12:13] op_sel_hi:[0,1]
	v_pk_mul_f32 v[4:5], v[0:1], v[4:5]
	v_pk_mul_f32 v[0:1], v[16:17], v[6:7] op_sel_hi:[0,1]
	v_pk_mul_f32 v[6:7], v[2:3], v[0:1]
	v_cvt_pk_bf16_f32 v0, v8, v9
	v_cvt_pk_bf16_f32 v1, v10, v11
	v_cvt_pk_bf16_f32 v2, v4, v5
	v_mad_i64_i32 v[4:5], s[26:27], v23, s51, v[112:113]
	v_lshl_add_u64 v[4:5], v[4:5], 0, v[114:115]
	s_mov_b64 s[26:27], s[20:21]
	v_cvt_pk_bf16_f32 v3, v6, v7
	global_store_dwordx4 v[4:5], v[0:3], off
	s_cbranch_vccz .LBB0_229
	s_waitcnt vmcnt(0)
	s_cmpk_gt_u32 s38, 0xff
	s_cbranch_scc1 .LBB0_236
	s_barrier

.LBB0_357:
	ds_read_b128 v[134:137], v190
	ds_read_b128 v[138:141], v190 offset:1024
	ds_read_b128 v[142:145], v190 offset:2048
	ds_read_b128 v[146:149], v190 offset:3072
	s_mov_b32 m0, s54
	v_lshl_add_u64 v[150:151], v[128:129], 0, s[34:35]
	ds_read_b128 v[166:169], v191
	ds_read_b128 v[170:173], v191 offset:1024
	ds_read_b128 v[174:177], v191 offset:2048
	ds_read_b128 v[178:181], v191 offset:3072
	ds_read_b128 v[194:197], v191 offset:4096
	ds_read_b128 v[198:201], v191 offset:5120
	ds_read_b128 v[202:205], v191 offset:6144
	ds_read_b128 v[206:209], v191 offset:7168
	global_load_lds_dwordx4 v[150:151], off
	s_mov_b32 m0, s55
	v_lshl_add_u64 v[150:151], v[130:131], 0, s[34:35]
	global_load_lds_dwordx4 v[150:151], off
	s_waitcnt lgkmcnt(8)
	s_barrier
	s_waitcnt lgkmcnt(0)
	s_setprio 1
	v_mfma_f32_16x16x32_bf16 v[116:119], v[134:137], v[166:169], v[116:119]
	s_add_i32 s36, s34, 0xfff50080
	v_mfma_f32_16x16x32_bf16 v[112:115], v[142:145], v[166:169], v[112:115]
	s_cmp_eq_u32 s67, 40
	v_mfma_f32_16x16x32_bf16 v[108:111], v[134:137], v[174:177], v[108:111]
	s_cselect_b32 s69, s27, s29
	v_mfma_f32_16x16x32_bf16 v[104:107], v[142:145], v[174:177], v[104:107]
	s_cselect_b32 s68, s26, s28
	v_mfma_f32_16x16x32_bf16 v[92:95], v[134:137], v[194:197], v[92:95]
	s_cselect_b32 s37, s9, s31
	v_mfma_f32_16x16x32_bf16 v[88:91], v[142:145], v[194:197], v[88:91]
	s_cselect_b32 s70, s8, s30
	v_mfma_f32_16x16x32_bf16 v[76:79], v[134:137], v[202:205], v[76:79]
	v_mfma_f32_16x16x32_bf16 v[72:75], v[142:145], v[202:205], v[72:75]
	v_mfma_f32_16x16x32_bf16 v[116:119], v[138:141], v[170:173], v[116:119]
	v_mfma_f32_16x16x32_bf16 v[112:115], v[146:149], v[170:173], v[112:115]
	v_mfma_f32_16x16x32_bf16 v[108:111], v[138:141], v[178:181], v[108:111]
	s_cselect_b32 s71, 0, s36
	v_mfma_f32_16x16x32_bf16 v[104:107], v[146:149], v[178:181], v[104:107]
	s_add_u32 s36, s70, s71
	v_mfma_f32_16x16x32_bf16 v[92:95], v[138:141], v[198:201], v[92:95]
	s_addc_u32 s37, s37, 0
	v_mfma_f32_16x16x32_bf16 v[88:91], v[146:149], v[198:201], v[88:91]
	v_lshl_add_u64 v[150:151], s[36:37], 0, v[156:157]
	v_mfma_f32_16x16x32_bf16 v[76:79], v[138:141], v[206:209], v[76:79]
	v_lshl_add_u64 v[182:183], s[36:37], 0, v[160:161]
	v_mfma_f32_16x16x32_bf16 v[72:75], v[146:149], v[206:209], v[72:75]
	s_setprio 0
	s_barrier
	s_mov_b32 m0, s56
	ds_read_b128 v[210:213], v192
	ds_read_b128 v[214:217], v192 offset:1024
	ds_read_b128 v[222:225], v192 offset:2048
	global_load_lds_dwordx4 v[150:151], off
	s_mov_b32 m0, s57
	ds_read_b128 v[226:229], v192 offset:3072
	global_load_lds_dwordx4 v[182:183], off
	s_barrier
	s_waitcnt lgkmcnt(0)
	s_setprio 1
	v_mfma_f32_16x16x32_bf16 v[124:127], v[210:213], v[166:169], v[124:127]
	v_mfma_f32_16x16x32_bf16 v[120:123], v[222:225], v[166:169], v[120:123]
	v_mfma_f32_16x16x32_bf16 v[100:103], v[210:213], v[174:177], v[100:103]
	v_mfma_f32_16x16x32_bf16 v[96:99], v[222:225], v[174:177], v[96:99]
	v_mfma_f32_16x16x32_bf16 v[84:87], v[210:213], v[194:197], v[84:87]
	v_mfma_f32_16x16x32_bf16 v[80:83], v[222:225], v[194:197], v[80:83]
	v_mfma_f32_16x16x32_bf16 v[68:71], v[210:213], v[202:205], v[68:71]
	v_mfma_f32_16x16x32_bf16 v[64:67], v[222:225], v[202:205], v[64:67]
	v_mfma_f32_16x16x32_bf16 v[124:127], v[214:217], v[170:173], v[124:127]
	v_mfma_f32_16x16x32_bf16 v[120:123], v[226:229], v[170:173], v[120:123]
	v_mfma_f32_16x16x32_bf16 v[100:103], v[214:217], v[178:181], v[100:103]
	v_mfma_f32_16x16x32_bf16 v[96:99], v[226:229], v[178:181], v[96:99]
	s_add_u32 s68, s68, s71
	v_mfma_f32_16x16x32_bf16 v[84:87], v[214:217], v[198:201], v[84:87]
	s_addc_u32 s69, s69, 0
	v_mfma_f32_16x16x32_bf16 v[80:83], v[226:229], v[198:201], v[80:83]
	v_lshl_add_u64 v[218:219], s[68:69], 0, v[154:155]
	v_mfma_f32_16x16x32_bf16 v[68:71], v[214:217], v[206:209], v[68:71]
	v_lshl_add_u64 v[230:231], s[68:69], 0, v[158:159]
	v_mfma_f32_16x16x32_bf16 v[64:67], v[226:229], v[206:209], v[64:67]
	s_setprio 0
	s_mov_b32 m0, s46
	s_barrier
	ds_read_b128 v[166:169], v191 offset:16384
	ds_read_b128 v[170:173], v191 offset:17408
	ds_read_b128 v[174:177], v191 offset:18432
	ds_read_b128 v[178:181], v191 offset:19456
	ds_read_b128 v[194:197], v191 offset:20480
	ds_read_b128 v[198:201], v191 offset:21504
	ds_read_b128 v[202:205], v191 offset:22528
	global_load_lds_dwordx4 v[218:219], off
	s_mov_b32 m0, s47
	ds_read_b128 v[206:209], v191 offset:23552
	global_load_lds_dwordx4 v[230:231], off
	s_barrier
	s_waitcnt lgkmcnt(0)
	s_setprio 1
	v_mfma_f32_16x16x32_bf16 v[52:55], v[134:137], v[166:169], v[52:55]
	v_mfma_f32_16x16x32_bf16 v[48:51], v[142:145], v[166:169], v[48:51]
	v_mfma_f32_16x16x32_bf16 v[44:47], v[134:137], v[174:177], v[44:47]
	v_mfma_f32_16x16x32_bf16 v[36:39], v[142:145], v[174:177], v[36:39]
	v_mfma_f32_16x16x32_bf16 v[28:31], v[134:137], v[194:197], v[28:31]
	v_mfma_f32_16x16x32_bf16 v[20:23], v[142:145], v[194:197], v[20:23]
	v_mfma_f32_16x16x32_bf16 v[12:15], v[134:137], v[202:205], v[12:15]
	v_mfma_f32_16x16x32_bf16 v[4:7], v[142:145], v[202:205], v[4:7]
	v_mfma_f32_16x16x32_bf16 v[52:55], v[138:141], v[170:173], v[52:55]
	v_mfma_f32_16x16x32_bf16 v[48:51], v[146:149], v[170:173], v[48:51]
	v_mfma_f32_16x16x32_bf16 v[44:47], v[138:141], v[178:181], v[44:47]
	v_mfma_f32_16x16x32_bf16 v[36:39], v[146:149], v[178:181], v[36:39]
	s_add_u32 s70, s36, 0xb0000
	v_mfma_f32_16x16x32_bf16 v[28:31], v[138:141], v[198:201], v[28:31]
	s_addc_u32 s71, s37, 0
	v_mfma_f32_16x16x32_bf16 v[20:23], v[146:149], v[198:201], v[20:23]
	v_lshl_add_u64 v[246:247], s[70:71], 0, v[156:157]
	v_mfma_f32_16x16x32_bf16 v[12:15], v[138:141], v[206:209], v[12:15]
	v_lshl_add_u64 v[248:249], s[70:71], 0, v[160:161]
	v_mfma_f32_16x16x32_bf16 v[4:7], v[146:149], v[206:209], v[4:7]
	s_setprio 0
	s_mov_b32 m0, s0
	s_barrier
	global_load_lds_dwordx4 v[246:247], off
	s_mov_b32 m0, s62
	s_nop 0
	global_load_lds_dwordx4 v[248:249], off
	s_waitcnt vmcnt(6)
	s_barrier
	s_setprio 1
	v_mfma_f32_16x16x32_bf16 v[60:63], v[210:213], v[166:169], v[60:63]
	v_mfma_f32_16x16x32_bf16 v[56:59], v[222:225], v[166:169], v[56:59]
	v_mfma_f32_16x16x32_bf16 v[40:43], v[210:213], v[174:177], v[40:43]
	v_mfma_f32_16x16x32_bf16 v[32:35], v[222:225], v[174:177], v[32:35]
	v_mfma_f32_16x16x32_bf16 v[24:27], v[210:213], v[194:197], v[24:27]
	v_mfma_f32_16x16x32_bf16 v[16:19], v[222:225], v[194:197], v[16:19]
	v_mfma_f32_16x16x32_bf16 v[8:11], v[210:213], v[202:205], v[8:11]
	v_mfma_f32_16x16x32_bf16 v[0:3], v[222:225], v[202:205], v[0:3]
	v_mfma_f32_16x16x32_bf16 v[60:63], v[214:217], v[170:173], v[60:63]
	v_mfma_f32_16x16x32_bf16 v[56:59], v[226:229], v[170:173], v[56:59]
	v_mfma_f32_16x16x32_bf16 v[40:43], v[214:217], v[178:181], v[40:43]
	v_mfma_f32_16x16x32_bf16 v[32:35], v[226:229], v[178:181], v[32:35]
	s_add_u32 s68, s68, 0xb0000
	v_mfma_f32_16x16x32_bf16 v[24:27], v[214:217], v[198:201], v[24:27]
	s_addc_u32 s69, s69, 0
	v_mfma_f32_16x16x32_bf16 v[16:19], v[226:229], v[198:201], v[16:19]
	v_lshl_add_u64 v[250:251], s[68:69], 0, v[154:155]
	v_mfma_f32_16x16x32_bf16 v[8:11], v[214:217], v[206:209], v[8:11]
	v_lshl_add_u64 v[252:253], s[68:69], 0, v[158:159]
	v_mfma_f32_16x16x32_bf16 v[0:3], v[226:229], v[206:209], v[0:3]
	s_setprio 0
	s_barrier
	ds_read_b128 v[134:137], v132
	ds_read_b128 v[138:141], v132 offset:1024
	ds_read_b128 v[142:145], v132 offset:2048
	ds_read_b128 v[146:149], v132 offset:3072
	s_mov_b32 m0, s48
	ds_read_b128 v[166:169], v191 offset:32768
	ds_read_b128 v[170:173], v191 offset:33792
	ds_read_b128 v[174:177], v191 offset:34816
	ds_read_b128 v[178:181], v191 offset:35840
	ds_read_b128 v[194:197], v191 offset:36864
	ds_read_b128 v[198:201], v191 offset:37888
	ds_read_b128 v[202:205], v191 offset:38912
	global_load_lds_dwordx4 v[250:251], off
	s_mov_b32 m0, s49
	ds_read_b128 v[206:209], v191 offset:39936
	global_load_lds_dwordx4 v[252:253], off
	s_waitcnt lgkmcnt(8)
	s_barrier
	s_waitcnt lgkmcnt(0)
	s_setprio 1
	v_mfma_f32_16x16x32_bf16 v[116:119], v[134:137], v[166:169], v[116:119]
	v_mfma_f32_16x16x32_bf16 v[112:115], v[142:145], v[166:169], v[112:115]
	v_mfma_f32_16x16x32_bf16 v[108:111], v[134:137], v[174:177], v[108:111]
	v_mfma_f32_16x16x32_bf16 v[104:107], v[142:145], v[174:177], v[104:107]
	v_mfma_f32_16x16x32_bf16 v[92:95], v[134:137], v[194:197], v[92:95]
	v_mfma_f32_16x16x32_bf16 v[88:91], v[142:145], v[194:197], v[88:91]
	v_mfma_f32_16x16x32_bf16 v[76:79], v[134:137], v[202:205], v[76:79]
	v_mfma_f32_16x16x32_bf16 v[72:75], v[142:145], v[202:205], v[72:75]
	v_mfma_f32_16x16x32_bf16 v[116:119], v[138:141], v[170:173], v[116:119]
	v_mfma_f32_16x16x32_bf16 v[112:115], v[146:149], v[170:173], v[112:115]
	v_mfma_f32_16x16x32_bf16 v[108:111], v[138:141], v[178:181], v[108:111]
	v_mfma_f32_16x16x32_bf16 v[104:107], v[146:149], v[178:181], v[104:107]
	v_mfma_f32_16x16x32_bf16 v[92:95], v[138:141], v[198:201], v[92:95]
	v_mfma_f32_16x16x32_bf16 v[88:91], v[146:149], v[198:201], v[88:91]
	v_lshl_add_u64 v[246:247], v[150:151], 0, s[10:11]
	v_mfma_f32_16x16x32_bf16 v[76:79], v[138:141], v[206:209], v[76:79]
	v_lshl_add_u64 v[248:249], v[182:183], 0, s[10:11]
	v_mfma_f32_16x16x32_bf16 v[72:75], v[146:149], v[206:209], v[72:75]
	s_setprio 0
	s_barrier
	s_mov_b32 m0, s63
	ds_read_b128 v[210:213], v133
	ds_read_b128 v[214:217], v133 offset:1024
	ds_read_b128 v[222:225], v133 offset:2048
	global_load_lds_dwordx4 v[246:247], off
	s_mov_b32 m0, s64
	ds_read_b128 v[226:229], v133 offset:3072
	global_load_lds_dwordx4 v[248:249], off
	s_barrier
	s_waitcnt lgkmcnt(0)
	s_setprio 1
	v_mfma_f32_16x16x32_bf16 v[124:127], v[210:213], v[166:169], v[124:127]
	v_mfma_f32_16x16x32_bf16 v[120:123], v[222:225], v[166:169], v[120:123]
	v_mfma_f32_16x16x32_bf16 v[100:103], v[210:213], v[174:177], v[100:103]
	v_mfma_f32_16x16x32_bf16 v[96:99], v[222:225], v[174:177], v[96:99]
	v_mfma_f32_16x16x32_bf16 v[84:87], v[210:213], v[194:197], v[84:87]
	v_mfma_f32_16x16x32_bf16 v[80:83], v[222:225], v[194:197], v[80:83]
	v_mfma_f32_16x16x32_bf16 v[68:71], v[210:213], v[202:205], v[68:71]
	v_mfma_f32_16x16x32_bf16 v[64:67], v[222:225], v[202:205], v[64:67]
	v_mfma_f32_16x16x32_bf16 v[124:127], v[214:217], v[170:173], v[124:127]
	v_mfma_f32_16x16x32_bf16 v[120:123], v[226:229], v[170:173], v[120:123]
	v_mfma_f32_16x16x32_bf16 v[100:103], v[214:217], v[178:181], v[100:103]
	v_mfma_f32_16x16x32_bf16 v[96:99], v[226:229], v[178:181], v[96:99]
	v_mfma_f32_16x16x32_bf16 v[84:87], v[214:217], v[198:201], v[84:87]
	v_mfma_f32_16x16x32_bf16 v[80:83], v[226:229], v[198:201], v[80:83]
	v_lshl_add_u64 v[250:251], v[218:219], 0, s[10:11]
	v_mfma_f32_16x16x32_bf16 v[68:71], v[214:217], v[206:209], v[68:71]
	v_lshl_add_u64 v[252:253], v[230:231], 0, s[10:11]
	v_mfma_f32_16x16x32_bf16 v[64:67], v[226:229], v[206:209], v[64:67]
	s_setprio 0
	s_mov_b32 m0, s51
	s_barrier
	ds_read_b128 v[166:169], v191 offset:49152
	ds_read_b128 v[170:173], v191 offset:50176
	ds_read_b128 v[174:177], v191 offset:51200
	ds_read_b128 v[178:181], v191 offset:52224
	ds_read_b128 v[194:197], v191 offset:53248
	ds_read_b128 v[198:201], v191 offset:54272
	ds_read_b128 v[202:205], v191 offset:55296
	global_load_lds_dwordx4 v[250:251], off
	s_mov_b32 m0, s52
	ds_read_b128 v[206:209], v191 offset:56320
	global_load_lds_dwordx4 v[252:253], off
	s_barrier
;     ...
;         G_PAIR(0, 1);
; #pragma unroll 1
;         for (int t = 2; t < nt; t += 2) G_PAIR(t, 0);
	s_waitcnt lgkmcnt(0)
	s_setprio 1
	v_mfma_f32_16x16x32_bf16 v[52:55], v[134:137], v[166:169], v[52:55]
	v_mfma_f32_16x16x32_bf16 v[48:51], v[142:145], v[166:169], v[48:51]
	v_mfma_f32_16x16x32_bf16 v[44:47], v[134:137], v[174:177], v[44:47]
	v_mfma_f32_16x16x32_bf16 v[36:39], v[142:145], v[174:177], v[36:39]
	v_mfma_f32_16x16x32_bf16 v[28:31], v[134:137], v[194:197], v[28:31]
	v_mfma_f32_16x16x32_bf16 v[20:23], v[142:145], v[194:197], v[20:23]
	v_mfma_f32_16x16x32_bf16 v[12:15], v[134:137], v[202:205], v[12:15]
	v_mfma_f32_16x16x32_bf16 v[4:7], v[142:145], v[202:205], v[4:7]
	v_mfma_f32_16x16x32_bf16 v[52:55], v[138:141], v[170:173], v[52:55]
	v_mfma_f32_16x16x32_bf16 v[48:51], v[146:149], v[170:173], v[48:51]
	v_mfma_f32_16x16x32_bf16 v[44:47], v[138:141], v[178:181], v[44:47]
	v_mfma_f32_16x16x32_bf16 v[36:39], v[146:149], v[178:181], v[36:39]
	s_add_u32 s36, s36, 0xb0080
	v_mfma_f32_16x16x32_bf16 v[28:31], v[138:141], v[198:201], v[28:31]
	s_addc_u32 s37, s37, 0
	v_mfma_f32_16x16x32_bf16 v[20:23], v[146:149], v[198:201], v[20:23]
	v_lshl_add_u64 v[246:247], s[36:37], 0, v[156:157]
	v_mfma_f32_16x16x32_bf16 v[12:15], v[138:141], v[206:209], v[12:15]
	v_lshl_add_u64 v[248:249], s[36:37], 0, v[160:161]
	v_mfma_f32_16x16x32_bf16 v[4:7], v[146:149], v[206:209], v[4:7]
	s_setprio 0
	s_mov_b32 m0, s65
	s_barrier
	global_load_lds_dwordx4 v[246:247], off
	s_mov_b32 m0, s66
	s_nop 0
	global_load_lds_dwordx4 v[248:249], off
	s_waitcnt vmcnt(6)
	s_barrier
	s_setprio 1
	v_mfma_f32_16x16x32_bf16 v[60:63], v[210:213], v[166:169], v[60:63]
	v_mfma_f32_16x16x32_bf16 v[56:59], v[222:225], v[166:169], v[56:59]
	v_mfma_f32_16x16x32_bf16 v[40:43], v[210:213], v[174:177], v[40:43]
	v_mfma_f32_16x16x32_bf16 v[32:35], v[222:225], v[174:177], v[32:35]
	v_mfma_f32_16x16x32_bf16 v[24:27], v[210:213], v[194:197], v[24:27]
	v_mfma_f32_16x16x32_bf16 v[16:19], v[222:225], v[194:197], v[16:19]
	v_mfma_f32_16x16x32_bf16 v[8:11], v[210:213], v[202:205], v[8:11]
	v_mfma_f32_16x16x32_bf16 v[0:3], v[222:225], v[202:205], v[0:3]
	v_mfma_f32_16x16x32_bf16 v[60:63], v[214:217], v[170:173], v[60:63]
	v_mfma_f32_16x16x32_bf16 v[56:59], v[226:229], v[170:173], v[56:59]
	v_mfma_f32_16x16x32_bf16 v[40:43], v[214:217], v[178:181], v[40:43]
	v_mfma_f32_16x16x32_bf16 v[32:35], v[226:229], v[178:181], v[32:35]
	v_mfma_f32_16x16x32_bf16 v[24:27], v[214:217], v[198:201], v[24:27]
	v_mfma_f32_16x16x32_bf16 v[16:19], v[226:229], v[198:201], v[16:19]
	v_mfma_f32_16x16x32_bf16 v[8:11], v[214:217], v[206:209], v[8:11]
	v_mfma_f32_16x16x32_bf16 v[0:3], v[226:229], v[206:209], v[0:3]
	s_setprio 0
	s_add_i32 s67, s67, 2
	s_add_u32 s34, s34, 0x100
	s_addc_u32 s35, s35, 0
	s_cmp_gt_u32 s67, 41
	s_barrier
	s_cbranch_scc0 .LBB0_357
; __device__ __forceinline__ unsigned pk2(float lo, float hi) { unsigned r; asm volatile("v_cvt_pk_bf16_f32 %0, %1, %2" : "=v"(r) : "v"(lo), "v"(hi)); return r; }
; __device__ __forceinline__ unsigned pk2(float lo, float hi) { return f2bf(lo) | (f2bf(hi) << 16); }
;     __device__ __forceinline__ void epi(const f32x4 (&acc)[2][2][4][2], const Unit& u, int wr, int wc, int fr, int fq) const {
;     ...
;         const int row0 = u.pm * 256 + wr * 64 + fr, col0 = u.pn * 256 + wc * 32 + 8 * fq;
; #pragma unroll
;         for (int ai = 0; ai < 2; ++ai) {
;             u32x4 xo[4][2];
; #pragma unroll
;             for (int m = 0; m < 4; ++m)
; #pragma unroll
;                 for (int bj = 0; bj < 2; ++bj) xo[m][bj] = *(const u32x4*)(xb + (size_t)(row0 + ai * 128 + m * 16) * D + col0 + bj * 128);
; #pragma unroll
;             for (int m = 0; m < 4; ++m) {
;                 const int row = row0 + ai * 128 + m * 16; const size_t off = (size_t)row * D + col0; float ss = 0.f;
; #pragma unroll
;                 for (int bj = 0; bj < 2; ++bj) {
;                     const u32x4 o = xo[m][bj]; const f32x4 a0v = acc[ai][bj][m][0], a1v = acc[ai][bj][m][1];
;                     const float v0 = bf_lo(o.x) + coef * a0v[0], v1 = bf_hi(o.x) + coef * a0v[1], v2 = bf_lo(o.y) + coef * a0v[2], v3 = bf_hi(o.y) + coef * a0v[3];
;                     const float v4 = bf_lo(o.z) + coef * a1v[0], v5 = bf_hi(o.z) + coef * a1v[1], v6 = bf_lo(o.w) + coef * a1v[2], v7 = bf_hi(o.w) + coef * a1v[3];
;                     u32x4 w; w.x = pk2(v0, v1); w.y = pk2(v2, v3); w.z = pk2(v4, v5); w.w = pk2(v6, v7);
;                     *(u32x4*)(xb + off + bj * 128) = w;
;                     ss += ((v0 * v0 + v1 * v1) + (v2 * v2 + v3 * v3)) + ((v4 * v4 + v5 * v5) + (v6 * v6 + v7 * v7));
;                 }
;                 ss += __shfl_xor(ss, 16); ss += __shfl_xor(ss, 32);
;                 if (fq == 0) rowss[(size_t)row * 32 + u.pn * 4 + wc] = ss;
	v_lshl_or_b32 v166, s40, 8, v189
	v_lshl_add_u32 v170, s61, 8, v153
	v_ashrrev_i32_e32 v167, 31, v166
	v_lshlrev_b64 v[202:203], 1, v[166:167]
	v_ashrrev_i32_e32 v171, 31, v170
	v_lshl_add_u64 v[168:169], s[20:21], 0, v[202:203]
	v_lshlrev_b64 v[204:205], 11, v[170:171]
	v_lshl_add_u64 v[128:129], v[168:169], 0, v[204:205]
	v_mov_b32_e32 v218, 0x40000
	v_mov_b32_e32 v219, 0
	v_lshl_add_u64 v[216:217], v[128:129], 0, v[218:219]
	v_mov_b32_e32 v218, 0x8000
	global_load_dwordx4 v[194:197], v[128:129], off
	global_load_dwordx4 v[198:201], v[128:129], off offset:256
	v_or_b32_e32 v180, 16, v170
	v_or_b32_e32 v176, 32, v170
	v_or_b32_e32 v172, 48, v170
	v_ashrrev_i32_e32 v181, 31, v180
	v_ashrrev_i32_e32 v177, 31, v176
	v_ashrrev_i32_e32 v173, 31, v172
	v_lshlrev_b64 v[182:183], 11, v[180:181]
	v_lshlrev_b64 v[178:179], 11, v[176:177]
	v_lshlrev_b64 v[174:175], 11, v[172:173]
	v_lshl_add_u64 v[128:129], v[168:169], 0, v[182:183]
	v_lshl_add_u64 v[130:131], v[168:169], 0, v[178:179]
	v_lshl_add_u64 v[206:207], v[168:169], 0, v[174:175]
	global_load_dwordx4 v[148:151], v[128:129], off
	global_load_dwordx4 v[144:147], v[128:129], off offset:256
	global_load_dwordx4 v[140:143], v[130:131], off
	global_load_dwordx4 v[136:139], v[130:131], off offset:256
	global_load_dwordx4 v[132:135], v[206:207], off
	s_nop 0
	global_load_dwordx4 v[128:131], v[206:207], off offset:256
	global_load_dwordx4 v[222:225], v[216:217], off
	global_load_dwordx4 v[226:229], v[216:217], off offset:256
	v_lshl_add_u64 v[216:217], v[216:217], 0, v[218:219]
	global_load_dwordx4 v[230:233], v[216:217], off
	global_load_dwordx4 v[234:237], v[216:217], off offset:256
	v_lshl_add_u64 v[216:217], v[216:217], 0, v[218:219]
	global_load_dwordx4 v[238:241], v[216:217], off
	global_load_dwordx4 v[242:245], v[216:217], off offset:256
	v_lshl_add_u64 v[216:217], v[216:217], 0, v[218:219]
	global_load_dwordx4 v[246:249], v[216:217], off
	global_load_dwordx4 v[250:253], v[216:217], off offset:256
	v_and_b32_e32 v206, 64, v193
	v_xor_b32_e32 v208, 16, v193
	v_add_u32_e32 v206, 64, v206
	v_cmp_lt_i32_e32 vcc, v208, v206
	s_waitcnt vmcnt(8)
	v_lshlrev_b32_e32 v209, 16, v195
	v_cndmask_b32_e32 v207, v193, v208, vcc
	v_lshlrev_b32_e32 v208, 16, v194
	v_and_b32_e32 v194, 0xffff0000, v194
	v_and_b32_e32 v195, 0xffff0000, v195
	v_lshlrev_b32_e32 v210, 16, v196
	v_and_b32_e32 v196, 0xffff0000, v196
	v_lshlrev_b32_e32 v211, 16, v197
	v_and_b32_e32 v197, 0xffff0000, v197
	v_lshlrev_b32_e32 v212, 16, v198
	v_and_b32_e32 v198, 0xffff0000, v198
	v_lshlrev_b32_e32 v213, 16, v199
	v_and_b32_e32 v199, 0xffff0000, v199
	v_lshlrev_b32_e32 v214, 16, v200
	v_and_b32_e32 v200, 0xffff0000, v200
	v_lshlrev_b32_e32 v215, 16, v201
	v_and_b32_e32 v201, 0xffff0000, v201
	v_fmac_f32_e32 v194, 0.5, v117
	v_fmac_f32_e32 v195, 0.5, v119
	v_fmac_f32_e32 v196, 0.5, v113
	v_fmac_f32_e32 v197, 0.5, v115
	v_fmac_f32_e32 v198, 0.5, v125
	v_fmac_f32_e32 v199, 0.5, v127
	v_fmac_f32_e32 v200, 0.5, v121
	v_fmac_f32_e32 v201, 0.5, v123
	v_fmac_f32_e32 v208, 0.5, v116
	v_fmac_f32_e32 v209, 0.5, v118
	v_fmac_f32_e32 v210, 0.5, v112
	v_fmac_f32_e32 v211, 0.5, v114
	v_fmac_f32_e32 v212, 0.5, v124
	v_fmac_f32_e32 v213, 0.5, v126
	v_fmac_f32_e32 v214, 0.5, v120
	v_fmac_f32_e32 v215, 0.5, v122
	v_mul_f32_e32 v112, v194, v194
	v_mul_f32_e32 v113, v195, v195
	v_mul_f32_e32 v118, v196, v196
	v_mul_f32_e32 v119, v197, v197
	v_mul_f32_e32 v120, v198, v198
	v_mul_f32_e32 v121, v199, v199
	v_mul_f32_e32 v122, v200, v200
	v_mul_f32_e32 v123, v201, v201
	v_fmac_f32_e32 v112, v208, v208
	v_fmac_f32_e32 v113, v209, v209
	v_fmac_f32_e32 v118, v210, v210
	v_fmac_f32_e32 v119, v211, v211
	v_fmac_f32_e32 v120, v212, v212
	v_fmac_f32_e32 v121, v213, v213
	v_fmac_f32_e32 v122, v214, v214
	v_fmac_f32_e32 v123, v215, v215
	v_add_f32_e32 v112, v112, v113
	v_add_f32_e32 v113, v118, v119
	v_add_f32_e32 v118, v120, v121
	v_add_f32_e32 v119, v122, v123
	v_add_f32_e32 v112, v112, v113
	v_add_f32_e32 v113, v118, v119
	v_add_f32_e32 v113, v112, v113
	v_lshlrev_b32_e32 v112, 2, v207
	ds_bpermute_b32 v122, v112, v113
	v_lshl_add_u64 v[118:119], s[20:21], 0, v[204:205]
	v_cvt_pk_bf16_f32 v114, v208, v194
	v_lshl_add_u64 v[120:121], v[118:119], 0, v[202:203]
	v_cvt_pk_bf16_f32 v115, v209, v195
	v_cvt_pk_bf16_f32 v116, v210, v196
	v_cvt_pk_bf16_f32 v117, v211, v197
	global_store_dwordx4 v[120:121], v[114:117], off
	s_waitcnt lgkmcnt(0)
	s_nop 0
	v_add_f32_e32 v114, v113, v122
	v_xor_b32_e32 v113, 32, v193
	v_cmp_lt_i32_e32 vcc, v113, v206
	v_cvt_pk_bf16_f32 v116, v212, v198
	v_cvt_pk_bf16_f32 v117, v213, v199
	v_cvt_pk_bf16_f32 v118, v214, v200
	v_cvt_pk_bf16_f32 v119, v215, v201
	global_store_dwordx4 v[120:121], v[116:119], off offset:256
	s_nop 0
	v_cndmask_b32_e32 v113, v193, v113, vcc
	v_lshlrev_b32_e32 v113, 2, v113
	ds_bpermute_b32 v115, v113, v114
	s_and_saveexec_b64 s[28:29], s[6:7]
	s_cbranch_execz .LBB0_360
	s_waitcnt lgkmcnt(0)
	v_add_f32_e32 v116, v114, v115
	s_lshl_b32 s30, s40, 2
	v_lshlrev_b64 v[114:115], 7, v[170:171]
	s_ashr_i32 s31, s30, 31
	v_lshl_add_u64 v[114:115], s[2:3], 0, v[114:115]
	v_lshl_add_u64 v[114:115], s[30:31], 2, v[114:115]
	s_lshl_b32 s0, s50, 2
	v_lshl_add_u64 v[114:115], v[114:115], 0, s[0:1]
	global_store_dword v[114:115], v116, off

.LBB0_580:
	ds_read_b128 v[150:153], v144
	ds_read_b128 v[154:157], v144 offset:1024
	ds_read_b128 v[158:161], v144 offset:2048
	ds_read_b128 v[162:165], v144 offset:3072
	s_mov_b32 m0, s1
	v_lshl_add_u64 v[198:199], v[138:139], 0, s[44:45]
	ds_read_b128 v[166:169], v145
	ds_read_b128 v[170:173], v145 offset:1024
	ds_read_b128 v[174:177], v145 offset:2048
	ds_read_b128 v[178:181], v145 offset:3072
	ds_read_b128 v[182:185], v145 offset:4096
	ds_read_b128 v[186:189], v145 offset:5120
	ds_read_b128 v[190:193], v145 offset:6144
	ds_read_b128 v[194:197], v145 offset:7168
	global_load_lds_dwordx4 v[198:199], off
	s_mov_b32 m0, s12
	v_lshl_add_u64 v[198:199], v[140:141], 0, s[44:45]
	global_load_lds_dwordx4 v[198:199], off
	s_waitcnt lgkmcnt(8)
	s_barrier
	s_waitcnt lgkmcnt(0)
	s_setprio 1
	v_mfma_f32_16x16x32_bf16 v[28:31], v[150:153], v[166:169], v[28:31]
	s_add_i32 s81, s44, 0xfffc0080
	v_mfma_f32_16x16x32_bf16 v[24:27], v[158:161], v[166:169], v[24:27]
	s_cmp_eq_u32 s80, 4
	v_mfma_f32_16x16x32_bf16 v[20:23], v[150:153], v[174:177], v[20:23]
	s_cselect_b64 s[46:47], -1, 0
	v_mfma_f32_16x16x32_bf16 v[16:19], v[158:161], v[174:177], v[16:19]
	s_and_b64 s[82:83], s[46:47], exec
	v_mfma_f32_16x16x32_bf16 v[12:15], v[150:153], v[182:185], v[12:15]
	s_cselect_b32 s83, s39, s5
	v_mfma_f32_16x16x32_bf16 v[8:11], v[158:161], v[182:185], v[8:11]
	s_cselect_b32 s82, s38, s4
	v_mfma_f32_16x16x32_bf16 v[4:7], v[150:153], v[190:193], v[4:7]
	s_cselect_b32 s81, 0, s81
	v_mfma_f32_16x16x32_bf16 v[0:3], v[158:161], v[190:193], v[0:3]
	s_and_b64 s[46:47], s[42:43], s[46:47]
	v_mfma_f32_16x16x32_bf16 v[28:31], v[154:157], v[170:173], v[28:31]
	s_and_b64 s[46:47], s[46:47], exec
	v_mfma_f32_16x16x32_bf16 v[24:27], v[162:165], v[170:173], v[24:27]
	s_cselect_b32 s47, s41, s7
	v_mfma_f32_16x16x32_bf16 v[20:23], v[154:157], v[178:181], v[20:23]
	s_cselect_b32 s46, s40, s6
	v_mfma_f32_16x16x32_bf16 v[16:19], v[162:165], v[178:181], v[16:19]
	s_add_u32 s46, s46, s81
	v_mfma_f32_16x16x32_bf16 v[12:15], v[154:157], v[186:189], v[12:15]
	s_addc_u32 s47, s47, 0
	v_mfma_f32_16x16x32_bf16 v[8:11], v[162:165], v[186:189], v[8:11]
	v_lshl_add_u64 v[214:215], s[46:47], 0, v[130:131]
	v_mfma_f32_16x16x32_bf16 v[4:7], v[154:157], v[194:197], v[4:7]
	v_lshl_add_u64 v[216:217], s[46:47], 0, v[128:129]
	v_mfma_f32_16x16x32_bf16 v[0:3], v[162:165], v[194:197], v[0:3]
	s_setprio 0
	s_barrier
	s_mov_b32 m0, s35
	ds_read_b128 v[198:201], v146
	ds_read_b128 v[202:205], v146 offset:1024
	ds_read_b128 v[206:209], v146 offset:2048
	global_load_lds_dwordx4 v[214:215], off
	s_mov_b32 m0, s73
	ds_read_b128 v[210:213], v146 offset:3072
	global_load_lds_dwordx4 v[216:217], off
	s_barrier
	s_waitcnt lgkmcnt(0)
	s_setprio 1
	v_mfma_f32_16x16x32_bf16 v[92:95], v[198:201], v[166:169], v[92:95]
	v_mfma_f32_16x16x32_bf16 v[88:91], v[206:209], v[166:169], v[88:91]
	v_mfma_f32_16x16x32_bf16 v[76:79], v[198:201], v[174:177], v[76:79]
	v_mfma_f32_16x16x32_bf16 v[72:75], v[206:209], v[174:177], v[72:75]
	v_mfma_f32_16x16x32_bf16 v[60:63], v[198:201], v[182:185], v[60:63]
	v_mfma_f32_16x16x32_bf16 v[56:59], v[206:209], v[182:185], v[56:59]
	v_mfma_f32_16x16x32_bf16 v[44:47], v[198:201], v[190:193], v[44:47]
	v_mfma_f32_16x16x32_bf16 v[40:43], v[206:209], v[190:193], v[40:43]
	v_mfma_f32_16x16x32_bf16 v[92:95], v[202:205], v[170:173], v[92:95]
	v_mfma_f32_16x16x32_bf16 v[88:91], v[210:213], v[170:173], v[88:91]
	v_mfma_f32_16x16x32_bf16 v[76:79], v[202:205], v[178:181], v[76:79]
	v_mfma_f32_16x16x32_bf16 v[72:75], v[210:213], v[178:181], v[72:75]
	s_add_u32 s82, s82, s81
	v_mfma_f32_16x16x32_bf16 v[60:63], v[202:205], v[186:189], v[60:63]
	s_addc_u32 s83, s83, 0
	v_mfma_f32_16x16x32_bf16 v[56:59], v[210:213], v[186:189], v[56:59]
	v_lshl_add_u64 v[218:219], s[82:83], 0, v[130:131]
	v_mfma_f32_16x16x32_bf16 v[44:47], v[202:205], v[194:197], v[44:47]
	v_lshl_add_u64 v[222:223], s[82:83], 0, v[128:129]
	v_mfma_f32_16x16x32_bf16 v[40:43], v[210:213], v[194:197], v[40:43]
	s_setprio 0
	s_mov_b32 m0, s52
	s_barrier
	ds_read_b128 v[166:169], v145 offset:16384
	ds_read_b128 v[170:173], v145 offset:17408
	ds_read_b128 v[174:177], v145 offset:18432
	ds_read_b128 v[178:181], v145 offset:19456
	ds_read_b128 v[182:185], v145 offset:20480
	ds_read_b128 v[186:189], v145 offset:21504
	ds_read_b128 v[190:193], v145 offset:22528
	global_load_lds_dwordx4 v[218:219], off
	s_mov_b32 m0, s55
	ds_read_b128 v[194:197], v145 offset:23552
	global_load_lds_dwordx4 v[222:223], off
	s_barrier
	s_waitcnt lgkmcnt(0)
	s_setprio 1
	v_mfma_f32_16x16x32_bf16 v[84:87], v[150:153], v[166:169], v[84:87]
	v_mfma_f32_16x16x32_bf16 v[80:83], v[158:161], v[166:169], v[80:83]
	v_mfma_f32_16x16x32_bf16 v[68:71], v[150:153], v[174:177], v[68:71]
	v_mfma_f32_16x16x32_bf16 v[64:67], v[158:161], v[174:177], v[64:67]
	v_mfma_f32_16x16x32_bf16 v[52:55], v[150:153], v[182:185], v[52:55]
	v_mfma_f32_16x16x32_bf16 v[48:51], v[158:161], v[182:185], v[48:51]
	v_mfma_f32_16x16x32_bf16 v[36:39], v[150:153], v[190:193], v[36:39]
	v_mfma_f32_16x16x32_bf16 v[32:35], v[158:161], v[190:193], v[32:35]
	v_mfma_f32_16x16x32_bf16 v[84:87], v[154:157], v[170:173], v[84:87]
	v_mfma_f32_16x16x32_bf16 v[80:83], v[162:165], v[170:173], v[80:83]
	v_mfma_f32_16x16x32_bf16 v[68:71], v[154:157], v[178:181], v[68:71]
	v_mfma_f32_16x16x32_bf16 v[64:67], v[162:165], v[178:181], v[64:67]
	s_add_u32 s84, s46, 0x40000
	v_mfma_f32_16x16x32_bf16 v[52:55], v[154:157], v[186:189], v[52:55]
	s_addc_u32 s85, s47, 0
	v_mfma_f32_16x16x32_bf16 v[48:51], v[162:165], v[186:189], v[48:51]
	v_lshl_add_u64 v[246:247], s[84:85], 0, v[130:131]
	v_mfma_f32_16x16x32_bf16 v[36:39], v[154:157], v[194:197], v[36:39]
	v_lshl_add_u64 v[248:249], s[84:85], 0, v[128:129]
	v_mfma_f32_16x16x32_bf16 v[32:35], v[162:165], v[194:197], v[32:35]
	s_setprio 0
	s_mov_b32 m0, s74
	s_barrier
	global_load_lds_dwordx4 v[246:247], off
	s_mov_b32 m0, s75
	s_nop 0
	global_load_lds_dwordx4 v[248:249], off
	s_waitcnt vmcnt(6)
	s_barrier
	s_setprio 1
	v_mfma_f32_16x16x32_bf16 v[124:127], v[198:201], v[166:169], v[124:127]
	v_mfma_f32_16x16x32_bf16 v[120:123], v[206:209], v[166:169], v[120:123]
	v_mfma_f32_16x16x32_bf16 v[116:119], v[198:201], v[174:177], v[116:119]
	v_mfma_f32_16x16x32_bf16 v[112:115], v[206:209], v[174:177], v[112:115]
	v_mfma_f32_16x16x32_bf16 v[108:111], v[198:201], v[182:185], v[108:111]
	v_mfma_f32_16x16x32_bf16 v[104:107], v[206:209], v[182:185], v[104:107]
	v_mfma_f32_16x16x32_bf16 v[100:103], v[198:201], v[190:193], v[100:103]
	v_mfma_f32_16x16x32_bf16 v[96:99], v[206:209], v[190:193], v[96:99]
	v_mfma_f32_16x16x32_bf16 v[124:127], v[202:205], v[170:173], v[124:127]
	v_mfma_f32_16x16x32_bf16 v[120:123], v[210:213], v[170:173], v[120:123]
	v_mfma_f32_16x16x32_bf16 v[116:119], v[202:205], v[178:181], v[116:119]
	v_mfma_f32_16x16x32_bf16 v[112:115], v[210:213], v[178:181], v[112:115]
	s_add_u32 s82, s82, 0x40000
	v_mfma_f32_16x16x32_bf16 v[108:111], v[202:205], v[186:189], v[108:111]
	s_addc_u32 s83, s83, 0
	v_mfma_f32_16x16x32_bf16 v[104:107], v[210:213], v[186:189], v[104:107]
	v_lshl_add_u64 v[250:251], s[82:83], 0, v[130:131]
	v_mfma_f32_16x16x32_bf16 v[100:103], v[202:205], v[194:197], v[100:103]
	v_lshl_add_u64 v[252:253], s[82:83], 0, v[128:129]
	v_mfma_f32_16x16x32_bf16 v[96:99], v[210:213], v[194:197], v[96:99]
	s_setprio 0
	s_barrier
	ds_read_b128 v[150:153], v147
	ds_read_b128 v[154:157], v147 offset:1024
	ds_read_b128 v[158:161], v147 offset:2048
	ds_read_b128 v[162:165], v147 offset:3072
	s_mov_b32 m0, s56
	ds_read_b128 v[166:169], v145 offset:32768
	ds_read_b128 v[170:173], v145 offset:33792
	ds_read_b128 v[174:177], v145 offset:34816
	ds_read_b128 v[178:181], v145 offset:35840
	ds_read_b128 v[182:185], v145 offset:36864
	ds_read_b128 v[186:189], v145 offset:37888
	ds_read_b128 v[190:193], v145 offset:38912
	global_load_lds_dwordx4 v[250:251], off
	s_mov_b32 m0, s57
	ds_read_b128 v[194:197], v145 offset:39936
	global_load_lds_dwordx4 v[252:253], off
	s_waitcnt lgkmcnt(8)
	s_barrier
	s_waitcnt lgkmcnt(0)
	s_setprio 1
	v_mfma_f32_16x16x32_bf16 v[28:31], v[150:153], v[166:169], v[28:31]
	v_mfma_f32_16x16x32_bf16 v[24:27], v[158:161], v[166:169], v[24:27]
	v_mfma_f32_16x16x32_bf16 v[20:23], v[150:153], v[174:177], v[20:23]
	v_mfma_f32_16x16x32_bf16 v[16:19], v[158:161], v[174:177], v[16:19]
	v_mfma_f32_16x16x32_bf16 v[12:15], v[150:153], v[182:185], v[12:15]
	v_mfma_f32_16x16x32_bf16 v[8:11], v[158:161], v[182:185], v[8:11]
	v_mfma_f32_16x16x32_bf16 v[4:7], v[150:153], v[190:193], v[4:7]
	v_mfma_f32_16x16x32_bf16 v[0:3], v[158:161], v[190:193], v[0:3]
	v_mfma_f32_16x16x32_bf16 v[28:31], v[154:157], v[170:173], v[28:31]
	v_mfma_f32_16x16x32_bf16 v[24:27], v[162:165], v[170:173], v[24:27]
	v_mfma_f32_16x16x32_bf16 v[20:23], v[154:157], v[178:181], v[20:23]
	v_mfma_f32_16x16x32_bf16 v[16:19], v[162:165], v[178:181], v[16:19]
	v_mfma_f32_16x16x32_bf16 v[12:15], v[154:157], v[186:189], v[12:15]
	v_mfma_f32_16x16x32_bf16 v[8:11], v[162:165], v[186:189], v[8:11]
	v_lshl_add_u64 v[246:247], v[214:215], 0, s[2:3]
	v_mfma_f32_16x16x32_bf16 v[4:7], v[154:157], v[194:197], v[4:7]
	v_lshl_add_u64 v[248:249], v[216:217], 0, s[2:3]
	v_mfma_f32_16x16x32_bf16 v[0:3], v[162:165], v[194:197], v[0:3]
	s_setprio 0
	s_barrier
	s_mov_b32 m0, s76
	ds_read_b128 v[198:201], v148
	ds_read_b128 v[202:205], v148 offset:1024
	ds_read_b128 v[206:209], v148 offset:2048
	global_load_lds_dwordx4 v[246:247], off
	s_mov_b32 m0, s77
	ds_read_b128 v[210:213], v148 offset:3072
	global_load_lds_dwordx4 v[248:249], off
	s_barrier
	s_waitcnt lgkmcnt(0)
	s_setprio 1
	v_mfma_f32_16x16x32_bf16 v[92:95], v[198:201], v[166:169], v[92:95]
	v_mfma_f32_16x16x32_bf16 v[88:91], v[206:209], v[166:169], v[88:91]
	v_mfma_f32_16x16x32_bf16 v[76:79], v[198:201], v[174:177], v[76:79]
	v_mfma_f32_16x16x32_bf16 v[72:75], v[206:209], v[174:177], v[72:75]
	v_mfma_f32_16x16x32_bf16 v[60:63], v[198:201], v[182:185], v[60:63]
	v_mfma_f32_16x16x32_bf16 v[56:59], v[206:209], v[182:185], v[56:59]
	v_mfma_f32_16x16x32_bf16 v[44:47], v[198:201], v[190:193], v[44:47]
	v_mfma_f32_16x16x32_bf16 v[40:43], v[206:209], v[190:193], v[40:43]
	v_mfma_f32_16x16x32_bf16 v[92:95], v[202:205], v[170:173], v[92:95]
	v_mfma_f32_16x16x32_bf16 v[88:91], v[210:213], v[170:173], v[88:91]
	v_mfma_f32_16x16x32_bf16 v[76:79], v[202:205], v[178:181], v[76:79]
	v_mfma_f32_16x16x32_bf16 v[72:75], v[210:213], v[178:181], v[72:75]
	v_mfma_f32_16x16x32_bf16 v[60:63], v[202:205], v[186:189], v[60:63]
	v_mfma_f32_16x16x32_bf16 v[56:59], v[210:213], v[186:189], v[56:59]
	v_lshl_add_u64 v[250:251], v[218:219], 0, s[2:3]
	v_mfma_f32_16x16x32_bf16 v[44:47], v[202:205], v[194:197], v[44:47]
	v_lshl_add_u64 v[252:253], v[222:223], 0, s[2:3]
	v_mfma_f32_16x16x32_bf16 v[40:43], v[210:213], v[194:197], v[40:43]
	s_setprio 0
	s_mov_b32 m0, s61
	s_barrier
	ds_read_b128 v[166:169], v145 offset:49152
	ds_read_b128 v[170:173], v145 offset:50176
	ds_read_b128 v[174:177], v145 offset:51200
	ds_read_b128 v[178:181], v145 offset:52224
	ds_read_b128 v[182:185], v145 offset:53248
	ds_read_b128 v[186:189], v145 offset:54272
	ds_read_b128 v[190:193], v145 offset:55296
	global_load_lds_dwordx4 v[250:251], off
	s_mov_b32 m0, s62
	ds_read_b128 v[194:197], v145 offset:56320
	global_load_lds_dwordx4 v[252:253], off
	s_barrier
;     ...
;         G_PAIR(0, 1);
; #pragma unroll 1
;         for (int t = 2; t < nt; t += 2) G_PAIR(t, 0);
;     __device__ __forceinline__ void epi(const f32x4 (&acc)[2][2][4][2], const Unit& u, int wr, int wc, int fr, int fq) const {
;         const int row0 = u.pm * 256 + wr * 64 + fr, col0 = wc * 32 + 4 * fq;
; #pragma unroll
;         for (int ai = 0; ai < 2; ++ai)
; #pragma unroll
;             for (int m = 0; m < 4; ++m) {
;                 float* rowp = Send + (size_t)u.pn * NG * NCH * 256 + ((size_t)u.g * NCH + row0 + ai * 128 + m * 16) * 256 + col0;
; #pragma unroll
;                 for (int bj = 0; bj < 2; ++bj)
; #pragma unroll
;                     for (int n = 0; n < 2; ++n) *(f32x4*)(rowp + bj * 128 + n * 16) = acc[ai][bj][m][n];
;             }
;     }
	s_waitcnt lgkmcnt(0)
	s_setprio 1
	v_mfma_f32_16x16x32_bf16 v[84:87], v[150:153], v[166:169], v[84:87]
	v_mfma_f32_16x16x32_bf16 v[80:83], v[158:161], v[166:169], v[80:83]
	v_mfma_f32_16x16x32_bf16 v[68:71], v[150:153], v[174:177], v[68:71]
	v_mfma_f32_16x16x32_bf16 v[64:67], v[158:161], v[174:177], v[64:67]
	v_mfma_f32_16x16x32_bf16 v[52:55], v[150:153], v[182:185], v[52:55]
	v_mfma_f32_16x16x32_bf16 v[48:51], v[158:161], v[182:185], v[48:51]
	v_mfma_f32_16x16x32_bf16 v[36:39], v[150:153], v[190:193], v[36:39]
	v_mfma_f32_16x16x32_bf16 v[32:35], v[158:161], v[190:193], v[32:35]
	v_mfma_f32_16x16x32_bf16 v[84:87], v[154:157], v[170:173], v[84:87]
	v_mfma_f32_16x16x32_bf16 v[80:83], v[162:165], v[170:173], v[80:83]
	v_mfma_f32_16x16x32_bf16 v[68:71], v[154:157], v[178:181], v[68:71]
	v_mfma_f32_16x16x32_bf16 v[64:67], v[162:165], v[178:181], v[64:67]
	s_add_u32 s46, s46, 0x40080
	v_mfma_f32_16x16x32_bf16 v[52:55], v[154:157], v[186:189], v[52:55]
	s_addc_u32 s47, s47, 0
	v_mfma_f32_16x16x32_bf16 v[48:51], v[162:165], v[186:189], v[48:51]
	v_lshl_add_u64 v[246:247], s[46:47], 0, v[130:131]
	v_mfma_f32_16x16x32_bf16 v[36:39], v[154:157], v[194:197], v[36:39]
	v_lshl_add_u64 v[248:249], s[46:47], 0, v[128:129]
	v_mfma_f32_16x16x32_bf16 v[32:35], v[162:165], v[194:197], v[32:35]
	s_setprio 0
	s_mov_b32 m0, s78
	s_barrier
	global_load_lds_dwordx4 v[246:247], off
	s_mov_b32 m0, s79
	s_nop 0
	global_load_lds_dwordx4 v[248:249], off
	s_waitcnt vmcnt(6)
	s_barrier
	s_setprio 1
	v_mfma_f32_16x16x32_bf16 v[124:127], v[198:201], v[166:169], v[124:127]
	v_mfma_f32_16x16x32_bf16 v[120:123], v[206:209], v[166:169], v[120:123]
	v_mfma_f32_16x16x32_bf16 v[116:119], v[198:201], v[174:177], v[116:119]
	v_mfma_f32_16x16x32_bf16 v[112:115], v[206:209], v[174:177], v[112:115]
	v_mfma_f32_16x16x32_bf16 v[108:111], v[198:201], v[182:185], v[108:111]
	v_mfma_f32_16x16x32_bf16 v[104:107], v[206:209], v[182:185], v[104:107]
	v_mfma_f32_16x16x32_bf16 v[100:103], v[198:201], v[190:193], v[100:103]
	v_mfma_f32_16x16x32_bf16 v[96:99], v[206:209], v[190:193], v[96:99]
	v_mfma_f32_16x16x32_bf16 v[124:127], v[202:205], v[170:173], v[124:127]
	v_mfma_f32_16x16x32_bf16 v[120:123], v[210:213], v[170:173], v[120:123]
	v_mfma_f32_16x16x32_bf16 v[116:119], v[202:205], v[178:181], v[116:119]
	v_mfma_f32_16x16x32_bf16 v[112:115], v[210:213], v[178:181], v[112:115]
	v_mfma_f32_16x16x32_bf16 v[108:111], v[202:205], v[186:189], v[108:111]
	v_mfma_f32_16x16x32_bf16 v[104:107], v[210:213], v[186:189], v[104:107]
	v_mfma_f32_16x16x32_bf16 v[100:103], v[202:205], v[194:197], v[100:103]
	v_mfma_f32_16x16x32_bf16 v[96:99], v[210:213], v[194:197], v[96:99]
	s_setprio 0
	s_add_i32 s80, s80, 2
	s_add_u32 s44, s44, 0x100
	s_addc_u32 s45, s45, 0
	s_cmp_gt_u32 s80, 5
	s_barrier
	s_cbranch_scc0 .LBB0_580
	s_lshl_b32 s1, s53, 25
	s_add_u32 s4, s59, s1
	s_addc_u32 s5, s60, 0
	s_ashr_i32 s1, s0, 31
	v_lshl_add_u32 v138, s54, 8, v142
	s_lshl_b64 s[0:1], s[0:1], 19
	v_ashrrev_i32_e32 v139, 31, v138
	s_add_u32 s0, s4, s0
	v_lshlrev_b64 v[138:139], 10, v[138:139]
	s_addc_u32 s1, s5, s1
	v_lshl_add_u64 v[138:139], s[0:1], 0, v[138:139]
	v_lshl_add_u64 v[138:139], v[138:139], 0, v[132:133]
	global_store_dwordx4 v[138:139], v[28:31], off
	global_store_dwordx4 v[138:139], v[24:27], off offset:64
	global_store_dwordx4 v[138:139], v[92:95], off offset:512
	global_store_dwordx4 v[138:139], v[88:91], off offset:576
	v_add_co_u32_e32 v26, vcc, s58, v138
	v_lshl_add_u64 v[24:25], v[138:139], 0, s[18:19]
	s_nop 0
	v_addc_co_u32_e32 v27, vcc, 0, v139, vcc
	global_store_dwordx4 v[26:27], v[20:23], off
	global_store_dwordx4 v[24:25], v[16:19], off offset:64
	global_store_dwordx4 v[24:25], v[76:79], off offset:512
	global_store_dwordx4 v[24:25], v[72:75], off offset:576
	v_add_co_u32_e32 v18, vcc, s63, v138
	v_lshl_add_u64 v[16:17], v[138:139], 0, s[20:21]
	s_nop 0
	v_addc_co_u32_e32 v19, vcc, 0, v139, vcc
	global_store_dwordx4 v[18:19], v[12:15], off
	global_store_dwordx4 v[16:17], v[8:11], off offset:64
	global_store_dwordx4 v[16:17], v[60:63], off offset:512
	global_store_dwordx4 v[16:17], v[56:59], off offset:576
	v_add_co_u32_e32 v10, vcc, s65, v138
	v_lshl_add_u64 v[8:9], v[138:139], 0, s[22:23]
	s_nop 0
	v_addc_co_u32_e32 v11, vcc, 0, v139, vcc
	global_store_dwordx4 v[10:11], v[4:7], off
	global_store_dwordx4 v[8:9], v[0:3], off offset:64
	global_store_dwordx4 v[8:9], v[44:47], off offset:512
	global_store_dwordx4 v[8:9], v[40:43], off offset:576
	v_add_co_u32_e32 v2, vcc, s67, v138
	v_lshl_add_u64 v[0:1], v[138:139], 0, s[24:25]
	s_nop 0
	v_addc_co_u32_e32 v3, vcc, 0, v139, vcc
	global_store_dwordx4 v[2:3], v[84:87], off
	global_store_dwordx4 v[0:1], v[80:83], off offset:64
	global_store_dwordx4 v[0:1], v[124:127], off offset:512
	global_store_dwordx4 v[0:1], v[120:123], off offset:576
	v_add_co_u32_e32 v2, vcc, s68, v138
	v_lshl_add_u64 v[0:1], v[138:139], 0, s[26:27]
	s_nop 0
	v_addc_co_u32_e32 v3, vcc, 0, v139, vcc
	global_store_dwordx4 v[2:3], v[68:71], off
	global_store_dwordx4 v[0:1], v[64:67], off offset:64
	global_store_dwordx4 v[0:1], v[116:119], off offset:512
	global_store_dwordx4 v[0:1], v[112:115], off offset:576
	v_add_co_u32_e32 v2, vcc, s69, v138
	v_lshl_add_u64 v[0:1], v[138:139], 0, s[28:29]
	s_nop 0
	v_addc_co_u32_e32 v3, vcc, 0, v139, vcc
	global_store_dwordx4 v[2:3], v[52:55], off
	global_store_dwordx4 v[0:1], v[48:51], off offset:64
	global_store_dwordx4 v[0:1], v[108:111], off offset:512
	global_store_dwordx4 v[0:1], v[104:107], off offset:576
	v_add_co_u32_e32 v2, vcc, 0x2c000, v138
	s_mov_b32 s54, s72
	s_nop 0
	v_addc_co_u32_e32 v3, vcc, 0, v139, vcc
	v_readlane_b32 s72, v254, 3
	v_readlane_b32 s74, v254, 5
	s_and_b64 vcc, exec, s[36:37]
	s_mov_b32 s0, s34
	s_mov_b32 s53, s71
	s_mov_b64 s[6:7], s[40:41]
	s_mov_b64 s[4:5], s[38:39]
	v_readlane_b32 s73, v254, 4
	v_readlane_b32 s75, v254, 6
	v_lshl_add_u64 v[0:1], v[138:139], 0, s[30:31]
	global_store_dwordx4 v[2:3], v[36:39], off
	global_store_dwordx4 v[0:1], v[32:35], off offset:64
	global_store_dwordx4 v[0:1], v[100:103], off offset:512
	global_store_dwordx4 v[0:1], v[96:99], off offset:576
	s_cbranch_vccz .LBB0_575
	s_waitcnt vmcnt(0)
	s_cmpk_gt_u32 s48, 0xff
	s_cbranch_scc1 .LBB0_584
	s_barrier

.LBB0_920:
	ds_read_b128 v[132:135], v172
	ds_read_b128 v[136:139], v172 offset:1024
	ds_read_b128 v[152:155], v172 offset:2048
	ds_read_b128 v[156:159], v172 offset:3072
	s_mov_b32 m0, s48
	v_lshl_add_u64 v[168:169], v[120:121], 0, s[30:31]
	ds_read_b128 v[160:163], v173
	ds_read_b128 v[164:167], v173 offset:1024
	ds_read_b128 v[178:181], v173 offset:2048
	ds_read_b128 v[182:185], v173 offset:3072
	ds_read_b128 v[186:189], v173 offset:4096
	ds_read_b128 v[190:193], v173 offset:5120
	ds_read_b128 v[194:197], v173 offset:6144
	ds_read_b128 v[198:201], v173 offset:7168
	global_load_lds_dwordx4 v[168:169], off
	s_mov_b32 m0, s49
	v_lshl_add_u64 v[168:169], v[122:123], 0, s[30:31]
	global_load_lds_dwordx4 v[168:169], off
	s_waitcnt lgkmcnt(8)
	s_barrier
	s_waitcnt lgkmcnt(0)
	s_setprio 1
	v_mfma_f32_16x16x32_bf16 v[116:119], v[132:135], v[160:163], v[116:119]
	s_add_i32 s19, s30, 0xfffc0080
	v_mfma_f32_16x16x32_bf16 v[112:115], v[152:155], v[160:163], v[112:115]
	s_cmp_eq_u32 s17, 12
	v_mfma_f32_16x16x32_bf16 v[100:103], v[132:135], v[178:181], v[100:103]
	s_cselect_b64 s[34:35], -1, 0
	v_mfma_f32_16x16x32_bf16 v[96:99], v[152:155], v[178:181], v[96:99]
	s_and_b64 s[60:61], s[34:35], exec
	v_mfma_f32_16x16x32_bf16 v[84:87], v[132:135], v[186:189], v[84:87]
	s_cselect_b32 s19, 0, s19
	v_mfma_f32_16x16x32_bf16 v[80:83], v[152:155], v[186:189], v[80:83]
	s_and_b64 s[34:35], s[28:29], s[34:35]
	v_mfma_f32_16x16x32_bf16 v[68:71], v[132:135], v[194:197], v[68:71]
	s_and_b64 s[34:35], s[34:35], exec
	v_mfma_f32_16x16x32_bf16 v[64:67], v[152:155], v[194:197], v[64:67]
	s_cselect_b32 s61, s21, s25
	v_mfma_f32_16x16x32_bf16 v[116:119], v[136:139], v[164:167], v[116:119]
	s_cselect_b32 s60, s20, s24
	v_mfma_f32_16x16x32_bf16 v[112:115], v[156:159], v[164:167], v[112:115]
	s_cselect_b32 s35, s23, s27
	v_mfma_f32_16x16x32_bf16 v[100:103], v[136:139], v[182:185], v[100:103]
	s_cselect_b32 s34, s22, s26
	v_mfma_f32_16x16x32_bf16 v[96:99], v[156:159], v[182:185], v[96:99]
	s_add_u32 s34, s34, s19
	v_mfma_f32_16x16x32_bf16 v[84:87], v[136:139], v[190:193], v[84:87]
	s_addc_u32 s35, s35, 0
	v_mfma_f32_16x16x32_bf16 v[80:83], v[156:159], v[190:193], v[80:83]
	v_lshl_add_u64 v[168:169], s[34:35], 0, v[144:145]
	v_mfma_f32_16x16x32_bf16 v[68:71], v[136:139], v[198:201], v[68:71]
	v_lshl_add_u64 v[218:219], s[34:35], 0, v[140:141]
	v_mfma_f32_16x16x32_bf16 v[64:67], v[156:159], v[198:201], v[64:67]
	s_setprio 0
	s_barrier
	s_mov_b32 m0, s50
	ds_read_b128 v[202:205], v174
	ds_read_b128 v[206:209], v174 offset:1024
	ds_read_b128 v[210:213], v174 offset:2048
	global_load_lds_dwordx4 v[168:169], off
	s_mov_b32 m0, s51
	ds_read_b128 v[214:217], v174 offset:3072
	global_load_lds_dwordx4 v[218:219], off
	s_barrier
	s_waitcnt lgkmcnt(0)
	s_setprio 1
	v_mfma_f32_16x16x32_bf16 v[128:131], v[202:205], v[160:163], v[128:131]
	v_mfma_f32_16x16x32_bf16 v[124:127], v[210:213], v[160:163], v[124:127]
	v_mfma_f32_16x16x32_bf16 v[108:111], v[202:205], v[178:181], v[108:111]
	v_mfma_f32_16x16x32_bf16 v[104:107], v[210:213], v[178:181], v[104:107]
	v_mfma_f32_16x16x32_bf16 v[92:95], v[202:205], v[186:189], v[92:95]
	v_mfma_f32_16x16x32_bf16 v[88:91], v[210:213], v[186:189], v[88:91]
	v_mfma_f32_16x16x32_bf16 v[76:79], v[202:205], v[194:197], v[76:79]
	v_mfma_f32_16x16x32_bf16 v[72:75], v[210:213], v[194:197], v[72:75]
	v_mfma_f32_16x16x32_bf16 v[128:131], v[206:209], v[164:167], v[128:131]
	v_mfma_f32_16x16x32_bf16 v[124:127], v[214:217], v[164:167], v[124:127]
	v_mfma_f32_16x16x32_bf16 v[108:111], v[206:209], v[182:185], v[108:111]
	v_mfma_f32_16x16x32_bf16 v[104:107], v[214:217], v[182:185], v[104:107]
	s_add_u32 s60, s60, s19
	v_mfma_f32_16x16x32_bf16 v[92:95], v[206:209], v[190:193], v[92:95]
	s_addc_u32 s61, s61, 0
	v_mfma_f32_16x16x32_bf16 v[88:91], v[214:217], v[190:193], v[88:91]
	v_lshl_add_u64 v[222:223], s[60:61], 0, v[146:147]
	v_mfma_f32_16x16x32_bf16 v[76:79], v[206:209], v[198:201], v[76:79]
	v_lshl_add_u64 v[224:225], s[60:61], 0, v[142:143]
	v_mfma_f32_16x16x32_bf16 v[72:75], v[214:217], v[198:201], v[72:75]
	s_setprio 0
	s_mov_b32 m0, s41
	s_barrier
	ds_read_b128 v[160:163], v173 offset:16384
	ds_read_b128 v[164:167], v173 offset:17408
	ds_read_b128 v[178:181], v173 offset:18432
	ds_read_b128 v[182:185], v173 offset:19456
	ds_read_b128 v[186:189], v173 offset:20480
	ds_read_b128 v[190:193], v173 offset:21504
	ds_read_b128 v[194:197], v173 offset:22528
	global_load_lds_dwordx4 v[222:223], off
	s_mov_b32 m0, s42
	ds_read_b128 v[198:201], v173 offset:23552
	global_load_lds_dwordx4 v[224:225], off
	s_barrier
	s_waitcnt lgkmcnt(0)
	s_setprio 1
	v_mfma_f32_16x16x32_bf16 v[52:55], v[132:135], v[160:163], v[52:55]
	v_mfma_f32_16x16x32_bf16 v[48:51], v[152:155], v[160:163], v[48:51]
	v_mfma_f32_16x16x32_bf16 v[36:39], v[132:135], v[178:181], v[36:39]
	v_mfma_f32_16x16x32_bf16 v[32:35], v[152:155], v[178:181], v[32:35]
	v_mfma_f32_16x16x32_bf16 v[20:23], v[132:135], v[186:189], v[20:23]
	v_mfma_f32_16x16x32_bf16 v[16:19], v[152:155], v[186:189], v[16:19]
	v_mfma_f32_16x16x32_bf16 v[4:7], v[132:135], v[194:197], v[4:7]
	v_mfma_f32_16x16x32_bf16 v[0:3], v[152:155], v[194:197], v[0:3]
	v_mfma_f32_16x16x32_bf16 v[52:55], v[136:139], v[164:167], v[52:55]
	v_mfma_f32_16x16x32_bf16 v[48:51], v[156:159], v[164:167], v[48:51]
	v_mfma_f32_16x16x32_bf16 v[36:39], v[136:139], v[182:185], v[36:39]
	v_mfma_f32_16x16x32_bf16 v[32:35], v[156:159], v[182:185], v[32:35]
	s_add_u32 s62, s34, 0x40000
	v_mfma_f32_16x16x32_bf16 v[20:23], v[136:139], v[190:193], v[20:23]
	s_addc_u32 s63, s35, 0
	v_mfma_f32_16x16x32_bf16 v[16:19], v[156:159], v[190:193], v[16:19]
	v_lshl_add_u64 v[246:247], s[62:63], 0, v[144:145]
	v_mfma_f32_16x16x32_bf16 v[4:7], v[136:139], v[198:201], v[4:7]
	v_lshl_add_u64 v[248:249], s[62:63], 0, v[140:141]
	v_mfma_f32_16x16x32_bf16 v[0:3], v[156:159], v[198:201], v[0:3]
	s_setprio 0
	s_mov_b32 m0, s52
	s_barrier
	global_load_lds_dwordx4 v[246:247], off
	s_mov_b32 m0, s53
	s_nop 0
	global_load_lds_dwordx4 v[248:249], off
	s_waitcnt vmcnt(6)
	s_barrier
	s_setprio 1
	v_mfma_f32_16x16x32_bf16 v[60:63], v[202:205], v[160:163], v[60:63]
	v_mfma_f32_16x16x32_bf16 v[56:59], v[210:213], v[160:163], v[56:59]
	v_mfma_f32_16x16x32_bf16 v[44:47], v[202:205], v[178:181], v[44:47]
	v_mfma_f32_16x16x32_bf16 v[40:43], v[210:213], v[178:181], v[40:43]
	v_mfma_f32_16x16x32_bf16 v[28:31], v[202:205], v[186:189], v[28:31]
	v_mfma_f32_16x16x32_bf16 v[24:27], v[210:213], v[186:189], v[24:27]
	v_mfma_f32_16x16x32_bf16 v[12:15], v[202:205], v[194:197], v[12:15]
	v_mfma_f32_16x16x32_bf16 v[8:11], v[210:213], v[194:197], v[8:11]
	v_mfma_f32_16x16x32_bf16 v[60:63], v[206:209], v[164:167], v[60:63]
	v_mfma_f32_16x16x32_bf16 v[56:59], v[214:217], v[164:167], v[56:59]
	v_mfma_f32_16x16x32_bf16 v[44:47], v[206:209], v[182:185], v[44:47]
	v_mfma_f32_16x16x32_bf16 v[40:43], v[214:217], v[182:185], v[40:43]
	s_add_u32 s60, s60, 0x40000
	v_mfma_f32_16x16x32_bf16 v[28:31], v[206:209], v[190:193], v[28:31]
	s_addc_u32 s61, s61, 0
	v_mfma_f32_16x16x32_bf16 v[24:27], v[214:217], v[190:193], v[24:27]
	v_lshl_add_u64 v[250:251], s[60:61], 0, v[146:147]
	v_mfma_f32_16x16x32_bf16 v[12:15], v[206:209], v[198:201], v[12:15]
	v_lshl_add_u64 v[252:253], s[60:61], 0, v[142:143]
	v_mfma_f32_16x16x32_bf16 v[8:11], v[214:217], v[198:201], v[8:11]
	s_setprio 0
	s_barrier
	ds_read_b128 v[132:135], v176
	ds_read_b128 v[136:139], v176 offset:1024
	ds_read_b128 v[152:155], v176 offset:2048
	ds_read_b128 v[156:159], v176 offset:3072
	s_mov_b32 m0, s43
	ds_read_b128 v[160:163], v173 offset:32768
	ds_read_b128 v[164:167], v173 offset:33792
	ds_read_b128 v[178:181], v173 offset:34816
	ds_read_b128 v[182:185], v173 offset:35840
	ds_read_b128 v[186:189], v173 offset:36864
	ds_read_b128 v[190:193], v173 offset:37888
	ds_read_b128 v[194:197], v173 offset:38912
	global_load_lds_dwordx4 v[250:251], off
	s_mov_b32 m0, s44
	ds_read_b128 v[198:201], v173 offset:39936
	global_load_lds_dwordx4 v[252:253], off
	s_waitcnt lgkmcnt(8)
	s_barrier
	s_waitcnt lgkmcnt(0)
	s_setprio 1
	v_mfma_f32_16x16x32_bf16 v[116:119], v[132:135], v[160:163], v[116:119]
	v_mfma_f32_16x16x32_bf16 v[112:115], v[152:155], v[160:163], v[112:115]
	v_mfma_f32_16x16x32_bf16 v[100:103], v[132:135], v[178:181], v[100:103]
	v_mfma_f32_16x16x32_bf16 v[96:99], v[152:155], v[178:181], v[96:99]
	v_mfma_f32_16x16x32_bf16 v[84:87], v[132:135], v[186:189], v[84:87]
	v_mfma_f32_16x16x32_bf16 v[80:83], v[152:155], v[186:189], v[80:83]
	v_mfma_f32_16x16x32_bf16 v[68:71], v[132:135], v[194:197], v[68:71]
	v_mfma_f32_16x16x32_bf16 v[64:67], v[152:155], v[194:197], v[64:67]
	v_mfma_f32_16x16x32_bf16 v[116:119], v[136:139], v[164:167], v[116:119]
	v_mfma_f32_16x16x32_bf16 v[112:115], v[156:159], v[164:167], v[112:115]
	v_mfma_f32_16x16x32_bf16 v[100:103], v[136:139], v[182:185], v[100:103]
	v_mfma_f32_16x16x32_bf16 v[96:99], v[156:159], v[182:185], v[96:99]
	v_mfma_f32_16x16x32_bf16 v[84:87], v[136:139], v[190:193], v[84:87]
	v_mfma_f32_16x16x32_bf16 v[80:83], v[156:159], v[190:193], v[80:83]
	v_lshl_add_u64 v[246:247], v[168:169], 0, s[6:7]
	v_mfma_f32_16x16x32_bf16 v[68:71], v[136:139], v[198:201], v[68:71]
	v_lshl_add_u64 v[248:249], v[218:219], 0, s[6:7]
	v_mfma_f32_16x16x32_bf16 v[64:67], v[156:159], v[198:201], v[64:67]
	s_setprio 0
	s_barrier
	s_mov_b32 m0, s54
	ds_read_b128 v[202:205], v177
	ds_read_b128 v[206:209], v177 offset:1024
	ds_read_b128 v[210:213], v177 offset:2048
	global_load_lds_dwordx4 v[246:247], off
	s_mov_b32 m0, s55
	ds_read_b128 v[214:217], v177 offset:3072
	global_load_lds_dwordx4 v[248:249], off
	s_barrier
	s_waitcnt lgkmcnt(0)
	s_setprio 1
	v_mfma_f32_16x16x32_bf16 v[128:131], v[202:205], v[160:163], v[128:131]
	v_mfma_f32_16x16x32_bf16 v[124:127], v[210:213], v[160:163], v[124:127]
	v_mfma_f32_16x16x32_bf16 v[108:111], v[202:205], v[178:181], v[108:111]
	v_mfma_f32_16x16x32_bf16 v[104:107], v[210:213], v[178:181], v[104:107]
	v_mfma_f32_16x16x32_bf16 v[92:95], v[202:205], v[186:189], v[92:95]
	v_mfma_f32_16x16x32_bf16 v[88:91], v[210:213], v[186:189], v[88:91]
	v_mfma_f32_16x16x32_bf16 v[76:79], v[202:205], v[194:197], v[76:79]
	v_mfma_f32_16x16x32_bf16 v[72:75], v[210:213], v[194:197], v[72:75]
	v_mfma_f32_16x16x32_bf16 v[128:131], v[206:209], v[164:167], v[128:131]
	v_mfma_f32_16x16x32_bf16 v[124:127], v[214:217], v[164:167], v[124:127]
	v_mfma_f32_16x16x32_bf16 v[108:111], v[206:209], v[182:185], v[108:111]
	v_mfma_f32_16x16x32_bf16 v[104:107], v[214:217], v[182:185], v[104:107]
	v_mfma_f32_16x16x32_bf16 v[92:95], v[206:209], v[190:193], v[92:95]
	v_mfma_f32_16x16x32_bf16 v[88:91], v[214:217], v[190:193], v[88:91]
	v_lshl_add_u64 v[250:251], v[222:223], 0, s[6:7]
	v_mfma_f32_16x16x32_bf16 v[76:79], v[206:209], v[198:201], v[76:79]
	v_lshl_add_u64 v[252:253], v[224:225], 0, s[6:7]
	v_mfma_f32_16x16x32_bf16 v[72:75], v[214:217], v[198:201], v[72:75]
	s_setprio 0
	s_mov_b32 m0, s46
	s_barrier
	ds_read_b128 v[160:163], v173 offset:49152
	ds_read_b128 v[164:167], v173 offset:50176
	ds_read_b128 v[178:181], v173 offset:51200
	ds_read_b128 v[182:185], v173 offset:52224
	ds_read_b128 v[186:189], v173 offset:53248
	ds_read_b128 v[190:193], v173 offset:54272
	ds_read_b128 v[194:197], v173 offset:55296
	global_load_lds_dwordx4 v[250:251], off
	s_mov_b32 m0, s47
	ds_read_b128 v[198:201], v173 offset:56320
	global_load_lds_dwordx4 v[252:253], off
	s_barrier
;     ...
;         G_PAIR(0, 1);
; #pragma unroll 1
;         for (int t = 2; t < nt; t += 2) G_PAIR(t, 0);
	s_waitcnt lgkmcnt(0)
	s_setprio 1
	v_mfma_f32_16x16x32_bf16 v[52:55], v[132:135], v[160:163], v[52:55]
	v_mfma_f32_16x16x32_bf16 v[48:51], v[152:155], v[160:163], v[48:51]
	v_mfma_f32_16x16x32_bf16 v[36:39], v[132:135], v[178:181], v[36:39]
	v_mfma_f32_16x16x32_bf16 v[32:35], v[152:155], v[178:181], v[32:35]
	v_mfma_f32_16x16x32_bf16 v[20:23], v[132:135], v[186:189], v[20:23]
	v_mfma_f32_16x16x32_bf16 v[16:19], v[152:155], v[186:189], v[16:19]
	v_mfma_f32_16x16x32_bf16 v[4:7], v[132:135], v[194:197], v[4:7]
	v_mfma_f32_16x16x32_bf16 v[0:3], v[152:155], v[194:197], v[0:3]
	v_mfma_f32_16x16x32_bf16 v[52:55], v[136:139], v[164:167], v[52:55]
	v_mfma_f32_16x16x32_bf16 v[48:51], v[156:159], v[164:167], v[48:51]
	v_mfma_f32_16x16x32_bf16 v[36:39], v[136:139], v[182:185], v[36:39]
	v_mfma_f32_16x16x32_bf16 v[32:35], v[156:159], v[182:185], v[32:35]
	s_add_u32 s34, s34, 0x40080
	v_mfma_f32_16x16x32_bf16 v[20:23], v[136:139], v[190:193], v[20:23]
	s_addc_u32 s35, s35, 0
	v_mfma_f32_16x16x32_bf16 v[16:19], v[156:159], v[190:193], v[16:19]
	v_lshl_add_u64 v[246:247], s[34:35], 0, v[144:145]
	v_mfma_f32_16x16x32_bf16 v[4:7], v[136:139], v[198:201], v[4:7]
	v_lshl_add_u64 v[248:249], s[34:35], 0, v[140:141]
	v_mfma_f32_16x16x32_bf16 v[0:3], v[156:159], v[198:201], v[0:3]
	s_setprio 0
	s_mov_b32 m0, s56
	s_barrier
	global_load_lds_dwordx4 v[246:247], off
	s_mov_b32 m0, s57
	s_nop 0
	global_load_lds_dwordx4 v[248:249], off
	s_waitcnt vmcnt(6)
	s_barrier
	s_setprio 1
	v_mfma_f32_16x16x32_bf16 v[60:63], v[202:205], v[160:163], v[60:63]
	v_mfma_f32_16x16x32_bf16 v[56:59], v[210:213], v[160:163], v[56:59]
	v_mfma_f32_16x16x32_bf16 v[44:47], v[202:205], v[178:181], v[44:47]
	v_mfma_f32_16x16x32_bf16 v[40:43], v[210:213], v[178:181], v[40:43]
	v_mfma_f32_16x16x32_bf16 v[28:31], v[202:205], v[186:189], v[28:31]
	v_mfma_f32_16x16x32_bf16 v[24:27], v[210:213], v[186:189], v[24:27]
	v_mfma_f32_16x16x32_bf16 v[12:15], v[202:205], v[194:197], v[12:15]
	v_mfma_f32_16x16x32_bf16 v[8:11], v[210:213], v[194:197], v[8:11]
	v_mfma_f32_16x16x32_bf16 v[60:63], v[206:209], v[164:167], v[60:63]
	v_mfma_f32_16x16x32_bf16 v[56:59], v[214:217], v[164:167], v[56:59]
	v_mfma_f32_16x16x32_bf16 v[44:47], v[206:209], v[182:185], v[44:47]
	v_mfma_f32_16x16x32_bf16 v[40:43], v[214:217], v[182:185], v[40:43]
	v_mfma_f32_16x16x32_bf16 v[28:31], v[206:209], v[190:193], v[28:31]
	v_mfma_f32_16x16x32_bf16 v[24:27], v[214:217], v[190:193], v[24:27]
	v_mfma_f32_16x16x32_bf16 v[12:15], v[206:209], v[198:201], v[12:15]
	v_mfma_f32_16x16x32_bf16 v[8:11], v[214:217], v[198:201], v[8:11]
	s_setprio 0
	s_add_i32 s17, s17, 2
	s_add_u32 s30, s30, 0x100
	s_addc_u32 s31, s31, 0
	s_cmp_gt_u32 s17, 13
	s_barrier
	s_cbranch_scc0 .LBB0_920
; __device__ __forceinline__ unsigned pk2(float lo, float hi) { unsigned r; asm volatile("v_cvt_pk_bf16_f32 %0, %1, %2" : "=v"(r) : "v"(lo), "v"(hi)); return r; }
; __device__ __forceinline__ unsigned pk2(float lo, float hi) { return f2bf(lo) | (f2bf(hi) << 16); }
; __device__ __forceinline__ float fast_sigmoid(float z) { return __builtin_amdgcn_rcpf(1.0f + __expf(-z)); }
;     __device__ __forceinline__ void epi(const f32x4 (&acc)[2][2][4][2], const Unit& u, int wr, int wc, int fr, int fq) const {
;         const int row0 = u.pm * 256 + wr * 64 + fr, col0 = u.pn * 128 + wc * 32 + 8 * fq;
; #pragma unroll
;         for (int ai = 0; ai < 2; ++ai) {
;             u32x4 xo[4];
; #pragma unroll
;             for (int m = 0; m < 4; ++m) xo[m] = *(const u32x4*)(xb + (size_t)(row0 + ai * 128 + m * 16) * D + col0);
; #pragma unroll
;             for (int m = 0; m < 4; ++m) {
;                 const int row = row0 + ai * 128 + m * 16; const size_t off = (size_t)row * D + col0;
;                 const u32x4 o = xo[m]; const f32x4 a0v = acc[ai][0][m][0], a1v = acc[ai][0][m][1], b0v = acc[ai][1][m][0], b1v = acc[ai][1][m][1];
;                 const float v0 = bf_lo(o.x) + coef * a0v[0] * fast_sigmoid(b0v[0]), v1 = bf_hi(o.x) + coef * a0v[1] * fast_sigmoid(b0v[1]);
;                 const float v2 = bf_lo(o.y) + coef * a0v[2] * fast_sigmoid(b0v[2]), v3 = bf_hi(o.y) + coef * a0v[3] * fast_sigmoid(b0v[3]);
;                 const float v4 = bf_lo(o.z) + coef * a1v[0] * fast_sigmoid(b1v[0]), v5 = bf_hi(o.z) + coef * a1v[1] * fast_sigmoid(b1v[1]);
;                 const float v6 = bf_lo(o.w) + coef * a1v[2] * fast_sigmoid(b1v[2]), v7 = bf_hi(o.w) + coef * a1v[3] * fast_sigmoid(b1v[3]);
;                 u32x4 w; w.x = pk2(v0, v1); w.y = pk2(v2, v3); w.z = pk2(v4, v5); w.w = pk2(v6, v7);
;                 *(u32x4*)(xb + off) = w;
;                 float ss = ((v0 * v0 + v1 * v1) + (v2 * v2 + v3 * v3)) + ((v4 * v4 + v5 * v5) + (v6 * v6 + v7 * v7));
;                 ss += __shfl_xor(ss, 16); ss += __shfl_xor(ss, 32);
;                 if (fq == 0) rowss[(size_t)row * 32 + u.pn * 4 + wc] = ss;
	v_lshl_or_b32 v152, s59, 7, v171
	v_lshl_add_u32 v156, s8, 8, v170
	v_ashrrev_i32_e32 v153, 31, v152
	v_lshlrev_b64 v[182:183], 1, v[152:153]
	v_ashrrev_i32_e32 v157, 31, v156
	v_lshl_add_u64 v[154:155], s[0:1], 0, v[182:183]
	v_lshlrev_b64 v[184:185], 11, v[156:157]
	v_lshl_add_u64 v[120:121], v[154:155], 0, v[184:185]
	v_mov_b32_e32 v236, 0x40000
	v_mov_b32_e32 v237, 0
	v_lshl_add_u64 v[234:235], v[120:121], 0, v[236:237]
	v_mov_b32_e32 v236, 0x8000
	global_load_dwordx4 v[178:181], v[120:121], off
	v_or_b32_e32 v166, 16, v156
	v_or_b32_e32 v162, 32, v156
	v_or_b32_e32 v158, 48, v156
	v_ashrrev_i32_e32 v167, 31, v166
	v_ashrrev_i32_e32 v163, 31, v162
	v_ashrrev_i32_e32 v159, 31, v158
	v_lshlrev_b64 v[168:169], 11, v[166:167]
	v_lshlrev_b64 v[164:165], 11, v[162:163]
	v_lshlrev_b64 v[160:161], 11, v[158:159]
	v_lshl_add_u64 v[120:121], v[154:155], 0, v[168:169]
	v_lshl_add_u64 v[122:123], v[154:155], 0, v[164:165]
	v_lshl_add_u64 v[186:187], v[154:155], 0, v[160:161]
	global_load_dwordx4 v[136:139], v[120:121], off
	global_load_dwordx4 v[132:135], v[122:123], off
	s_nop 0
	global_load_dwordx4 v[120:123], v[186:187], off
	global_load_dwordx4 v[238:241], v[234:235], off
	v_lshl_add_u64 v[234:235], v[234:235], 0, v[236:237]
	global_load_dwordx4 v[242:245], v[234:235], off
	v_lshl_add_u64 v[234:235], v[234:235], 0, v[236:237]
	global_load_dwordx4 v[246:249], v[234:235], off
	v_lshl_add_u64 v[234:235], v[234:235], 0, v[236:237]
	global_load_dwordx4 v[250:253], v[234:235], off
	v_mul_f32_e32 v129, 0xbfb8aa3b, v129
	v_mul_f32_e32 v131, 0xbfb8aa3b, v131
	v_mul_f32_e32 v125, 0xbfb8aa3b, v125
	v_mul_f32_e32 v127, 0xbfb8aa3b, v127
	v_mul_f32_e32 v128, 0xbfb8aa3b, v128
	v_mul_f32_e32 v130, 0xbfb8aa3b, v130
	v_mul_f32_e32 v124, 0xbfb8aa3b, v124
	v_mul_f32_e32 v126, 0xbfb8aa3b, v126
	v_exp_f32_e32 v129, v129
	v_exp_f32_e32 v131, v131
	v_exp_f32_e32 v125, v125
	v_exp_f32_e32 v127, v127
	v_exp_f32_e32 v128, v128
	v_exp_f32_e32 v130, v130
	v_exp_f32_e32 v189, v124
	v_exp_f32_e32 v126, v126
	v_and_b32_e32 v187, 64, v175
	v_xor_b32_e32 v186, 16, v175
	v_add_u32_e32 v187, 64, v187
	v_cmp_lt_i32_e32 vcc, v186, v187
	v_add_f32_e32 v129, 1.0, v129
	v_add_f32_e32 v131, 1.0, v131
	v_add_f32_e32 v125, 1.0, v125
	v_add_f32_e32 v127, 1.0, v127
	v_cndmask_b32_e32 v124, v175, v186, vcc
	v_add_f32_e32 v128, 1.0, v128
	v_add_f32_e32 v130, 1.0, v130
	v_add_f32_e32 v186, 1.0, v189
	v_add_f32_e32 v126, 1.0, v126
	v_rcp_f32_e32 v129, v129
	v_rcp_f32_e32 v131, v131
	v_rcp_f32_e32 v125, v125
	v_rcp_f32_e32 v127, v127
	v_rcp_f32_e32 v128, v128
	v_rcp_f32_e32 v130, v130
	v_rcp_f32_e32 v186, v186
	v_rcp_f32_e32 v126, v126
	v_lshlrev_b32_e32 v124, 2, v124
	v_xor_b32_e32 v188, 32, v175
	v_cmp_lt_i32_e32 vcc, v188, v187
	s_lshl_b32 s24, s59, 2
	s_ashr_i32 s25, s24, 31
	s_waitcnt vmcnt(4)
	v_lshlrev_b32_e32 v189, 16, v178
	v_and_b32_e32 v178, 0xffff0000, v178
	v_lshlrev_b32_e32 v190, 16, v179
	v_and_b32_e32 v179, 0xffff0000, v179
	v_lshlrev_b32_e32 v191, 16, v180
	v_and_b32_e32 v180, 0xffff0000, v180
	v_lshlrev_b32_e32 v192, 16, v181
	v_and_b32_e32 v181, 0xffff0000, v181
	v_fmac_f32_e32 v178, v117, v129
	v_fmac_f32_e32 v179, v119, v131
	v_fmac_f32_e32 v180, v113, v125
	v_fmac_f32_e32 v181, v115, v127
	v_fmac_f32_e32 v189, v116, v128
	v_fmac_f32_e32 v190, v118, v130
	v_fmac_f32_e32 v191, v112, v186
	v_fmac_f32_e32 v192, v114, v126
	v_mul_f32_e32 v112, v178, v178
	v_mul_f32_e32 v113, v179, v179
	v_mul_f32_e32 v114, v180, v180
	v_mul_f32_e32 v115, v181, v181
	v_fmac_f32_e32 v112, v189, v189
	v_fmac_f32_e32 v113, v190, v190
	v_fmac_f32_e32 v114, v191, v191
	v_fmac_f32_e32 v115, v192, v192
	v_add_f32_e32 v112, v112, v113
	v_add_f32_e32 v113, v114, v115
	v_add_f32_e32 v112, v112, v113
	ds_bpermute_b32 v113, v124, v112
	v_lshl_add_u64 v[126:127], s[0:1], 0, v[184:185]
	v_lshl_add_u64 v[126:127], v[126:127], 0, v[182:183]
	v_cvt_pk_bf16_f32 v116, v189, v178
	v_cvt_pk_bf16_f32 v117, v190, v179
	s_waitcnt lgkmcnt(0)
	v_add_f32_e32 v113, v112, v113
	v_cndmask_b32_e32 v112, v175, v188, vcc
	v_lshlrev_b32_e32 v112, 2, v112
	ds_bpermute_b32 v114, v112, v113
	v_cvt_pk_bf16_f32 v118, v191, v180
	v_cvt_pk_bf16_f32 v119, v192, v181
	global_store_dwordx4 v[126:127], v[116:119], off
	s_and_saveexec_b64 s[26:27], s[4:5]
	s_cbranch_execz .LBB0_923
	v_lshlrev_b64 v[116:117], 7, v[156:157]
	v_lshl_add_u64 v[116:117], s[2:3], 0, v[116:117]
	v_lshl_add_u64 v[116:117], s[24:25], 2, v[116:117]
	s_lshl_b32 s8, s45, 2
	v_lshl_add_u64 v[116:117], v[116:117], 0, s[8:9]
	s_waitcnt lgkmcnt(0)
	v_add_f32_e32 v113, v113, v114
	global_store_dword v[116:117], v113, off

.LBB0_1906:
	ds_read_b128 v[134:137], v185
	ds_read_b128 v[138:141], v185 offset:1024
	ds_read_b128 v[142:145], v185 offset:2048
	ds_read_b128 v[146:149], v185 offset:3072
	s_mov_b32 m0, s45
	v_lshl_add_u64 v[150:151], v[128:129], 0, s[24:25]
	ds_read_b128 v[164:167], v186
	ds_read_b128 v[168:171], v186 offset:1024
	ds_read_b128 v[172:175], v186 offset:2048
	ds_read_b128 v[176:179], v186 offset:3072
	ds_read_b128 v[190:193], v186 offset:4096
	ds_read_b128 v[194:197], v186 offset:5120
	ds_read_b128 v[198:201], v186 offset:6144
	ds_read_b128 v[202:205], v186 offset:7168
	global_load_lds_dwordx4 v[150:151], off
	s_mov_b32 m0, s46
	v_lshl_add_u64 v[150:151], v[130:131], 0, s[24:25]
	global_load_lds_dwordx4 v[150:151], off
	s_waitcnt lgkmcnt(8)
	s_barrier
	s_waitcnt lgkmcnt(0)
	s_setprio 1
	v_mfma_f32_16x16x32_bf16 v[116:119], v[134:137], v[164:167], v[116:119]
	s_add_i32 s26, s24, 0xfff50080
	v_mfma_f32_16x16x32_bf16 v[112:115], v[142:145], v[164:167], v[112:115]
	s_cmp_eq_u32 s58, 40
	v_mfma_f32_16x16x32_bf16 v[108:111], v[134:137], v[172:175], v[108:111]
	s_cselect_b32 s59, s19, s21
	v_mfma_f32_16x16x32_bf16 v[104:107], v[142:145], v[172:175], v[104:107]
	s_cselect_b32 s60, s18, s20
	v_mfma_f32_16x16x32_bf16 v[92:95], v[134:137], v[190:193], v[92:95]
	s_cselect_b32 s27, s7, s23
	v_mfma_f32_16x16x32_bf16 v[88:91], v[142:145], v[190:193], v[88:91]
	s_cselect_b32 s61, s6, s22
	v_mfma_f32_16x16x32_bf16 v[76:79], v[134:137], v[198:201], v[76:79]
	v_mfma_f32_16x16x32_bf16 v[72:75], v[142:145], v[198:201], v[72:75]
	v_mfma_f32_16x16x32_bf16 v[116:119], v[138:141], v[168:171], v[116:119]
	v_mfma_f32_16x16x32_bf16 v[112:115], v[146:149], v[168:171], v[112:115]
	v_mfma_f32_16x16x32_bf16 v[108:111], v[138:141], v[176:179], v[108:111]
	s_cselect_b32 s62, 0, s26
	v_mfma_f32_16x16x32_bf16 v[104:107], v[146:149], v[176:179], v[104:107]
	s_add_u32 s26, s61, s62
	v_mfma_f32_16x16x32_bf16 v[92:95], v[138:141], v[194:197], v[92:95]
	s_addc_u32 s27, s27, 0
	v_mfma_f32_16x16x32_bf16 v[88:91], v[146:149], v[194:197], v[88:91]
	v_lshl_add_u64 v[150:151], s[26:27], 0, v[154:155]
	v_mfma_f32_16x16x32_bf16 v[76:79], v[138:141], v[202:205], v[76:79]
	v_lshl_add_u64 v[180:181], s[26:27], 0, v[158:159]
	v_mfma_f32_16x16x32_bf16 v[72:75], v[146:149], v[202:205], v[72:75]
	s_setprio 0
	s_barrier
	s_mov_b32 m0, s47
	ds_read_b128 v[206:209], v187
	ds_read_b128 v[210:213], v187 offset:1024
	ds_read_b128 v[214:217], v187 offset:2048
	global_load_lds_dwordx4 v[150:151], off
	s_mov_b32 m0, s48
	ds_read_b128 v[222:225], v187 offset:3072
	global_load_lds_dwordx4 v[180:181], off
	s_barrier
	s_waitcnt lgkmcnt(0)
	s_setprio 1
	v_mfma_f32_16x16x32_bf16 v[124:127], v[206:209], v[164:167], v[124:127]
	v_mfma_f32_16x16x32_bf16 v[120:123], v[214:217], v[164:167], v[120:123]
	v_mfma_f32_16x16x32_bf16 v[100:103], v[206:209], v[172:175], v[100:103]
	v_mfma_f32_16x16x32_bf16 v[96:99], v[214:217], v[172:175], v[96:99]
	v_mfma_f32_16x16x32_bf16 v[84:87], v[206:209], v[190:193], v[84:87]
	v_mfma_f32_16x16x32_bf16 v[80:83], v[214:217], v[190:193], v[80:83]
	v_mfma_f32_16x16x32_bf16 v[68:71], v[206:209], v[198:201], v[68:71]
	v_mfma_f32_16x16x32_bf16 v[64:67], v[214:217], v[198:201], v[64:67]
	v_mfma_f32_16x16x32_bf16 v[124:127], v[210:213], v[168:171], v[124:127]
	v_mfma_f32_16x16x32_bf16 v[120:123], v[222:225], v[168:171], v[120:123]
	v_mfma_f32_16x16x32_bf16 v[100:103], v[210:213], v[176:179], v[100:103]
	v_mfma_f32_16x16x32_bf16 v[96:99], v[222:225], v[176:179], v[96:99]
	s_add_u32 s60, s60, s62
	v_mfma_f32_16x16x32_bf16 v[84:87], v[210:213], v[194:197], v[84:87]
	s_addc_u32 s61, s59, 0
	v_mfma_f32_16x16x32_bf16 v[80:83], v[222:225], v[194:197], v[80:83]
	v_lshl_add_u64 v[218:219], s[60:61], 0, v[152:153]
	v_mfma_f32_16x16x32_bf16 v[68:71], v[210:213], v[202:205], v[68:71]
	v_lshl_add_u64 v[226:227], s[60:61], 0, v[156:157]
	v_mfma_f32_16x16x32_bf16 v[64:67], v[222:225], v[202:205], v[64:67]
	s_setprio 0
	s_mov_b32 m0, s37
	s_barrier
	ds_read_b128 v[164:167], v186 offset:16384
	ds_read_b128 v[168:171], v186 offset:17408
	ds_read_b128 v[172:175], v186 offset:18432
	ds_read_b128 v[176:179], v186 offset:19456
	ds_read_b128 v[190:193], v186 offset:20480
	ds_read_b128 v[194:197], v186 offset:21504
	ds_read_b128 v[198:201], v186 offset:22528
	global_load_lds_dwordx4 v[218:219], off
	s_mov_b32 m0, s38
	ds_read_b128 v[202:205], v186 offset:23552
	global_load_lds_dwordx4 v[226:227], off
	s_barrier
	s_waitcnt lgkmcnt(0)
	s_setprio 1
	v_mfma_f32_16x16x32_bf16 v[52:55], v[134:137], v[164:167], v[52:55]
	v_mfma_f32_16x16x32_bf16 v[48:51], v[142:145], v[164:167], v[48:51]
	v_mfma_f32_16x16x32_bf16 v[44:47], v[134:137], v[172:175], v[44:47]
	v_mfma_f32_16x16x32_bf16 v[36:39], v[142:145], v[172:175], v[36:39]
	v_mfma_f32_16x16x32_bf16 v[28:31], v[134:137], v[190:193], v[28:31]
	v_mfma_f32_16x16x32_bf16 v[20:23], v[142:145], v[190:193], v[20:23]
	v_mfma_f32_16x16x32_bf16 v[12:15], v[134:137], v[198:201], v[12:15]
	v_mfma_f32_16x16x32_bf16 v[4:7], v[142:145], v[198:201], v[4:7]
	v_mfma_f32_16x16x32_bf16 v[52:55], v[138:141], v[168:171], v[52:55]
	v_mfma_f32_16x16x32_bf16 v[48:51], v[146:149], v[168:171], v[48:51]
	v_mfma_f32_16x16x32_bf16 v[44:47], v[138:141], v[176:179], v[44:47]
	v_mfma_f32_16x16x32_bf16 v[36:39], v[146:149], v[176:179], v[36:39]
	s_add_u32 s62, s26, 0xb0000
	v_mfma_f32_16x16x32_bf16 v[28:31], v[138:141], v[194:197], v[28:31]
	s_addc_u32 s63, s27, 0
	v_mfma_f32_16x16x32_bf16 v[20:23], v[146:149], v[194:197], v[20:23]
	v_lshl_add_u64 v[246:247], s[62:63], 0, v[154:155]
	v_mfma_f32_16x16x32_bf16 v[12:15], v[138:141], v[202:205], v[12:15]
	v_lshl_add_u64 v[248:249], s[62:63], 0, v[158:159]
	v_mfma_f32_16x16x32_bf16 v[4:7], v[146:149], v[202:205], v[4:7]
	s_setprio 0
	s_mov_b32 m0, s52
	s_barrier
	global_load_lds_dwordx4 v[246:247], off
	s_mov_b32 m0, s53
	s_nop 0
	global_load_lds_dwordx4 v[248:249], off
	s_waitcnt vmcnt(6)
	s_barrier
	s_setprio 1
	v_mfma_f32_16x16x32_bf16 v[60:63], v[206:209], v[164:167], v[60:63]
	v_mfma_f32_16x16x32_bf16 v[56:59], v[214:217], v[164:167], v[56:59]
	v_mfma_f32_16x16x32_bf16 v[40:43], v[206:209], v[172:175], v[40:43]
	v_mfma_f32_16x16x32_bf16 v[32:35], v[214:217], v[172:175], v[32:35]
	v_mfma_f32_16x16x32_bf16 v[24:27], v[206:209], v[190:193], v[24:27]
	v_mfma_f32_16x16x32_bf16 v[16:19], v[214:217], v[190:193], v[16:19]
	v_mfma_f32_16x16x32_bf16 v[8:11], v[206:209], v[198:201], v[8:11]
	v_mfma_f32_16x16x32_bf16 v[0:3], v[214:217], v[198:201], v[0:3]
	v_mfma_f32_16x16x32_bf16 v[60:63], v[210:213], v[168:171], v[60:63]
	v_mfma_f32_16x16x32_bf16 v[56:59], v[222:225], v[168:171], v[56:59]
	v_mfma_f32_16x16x32_bf16 v[40:43], v[210:213], v[176:179], v[40:43]
	v_mfma_f32_16x16x32_bf16 v[32:35], v[222:225], v[176:179], v[32:35]
	s_add_u32 s60, s60, 0xb0000
	v_mfma_f32_16x16x32_bf16 v[24:27], v[210:213], v[194:197], v[24:27]
	s_addc_u32 s61, s61, 0
	v_mfma_f32_16x16x32_bf16 v[16:19], v[222:225], v[194:197], v[16:19]
	v_lshl_add_u64 v[250:251], s[60:61], 0, v[152:153]
	v_mfma_f32_16x16x32_bf16 v[8:11], v[210:213], v[202:205], v[8:11]
	v_lshl_add_u64 v[252:253], s[60:61], 0, v[156:157]
	v_mfma_f32_16x16x32_bf16 v[0:3], v[222:225], v[202:205], v[0:3]
	s_setprio 0
	s_barrier
	ds_read_b128 v[134:137], v132
	ds_read_b128 v[138:141], v132 offset:1024
	ds_read_b128 v[142:145], v132 offset:2048
	ds_read_b128 v[146:149], v132 offset:3072
	s_mov_b32 m0, s39
	ds_read_b128 v[164:167], v186 offset:32768
	ds_read_b128 v[168:171], v186 offset:33792
	ds_read_b128 v[172:175], v186 offset:34816
	ds_read_b128 v[176:179], v186 offset:35840
	ds_read_b128 v[190:193], v186 offset:36864
	ds_read_b128 v[194:197], v186 offset:37888
	ds_read_b128 v[198:201], v186 offset:38912
	global_load_lds_dwordx4 v[250:251], off
	s_mov_b32 m0, s40
	ds_read_b128 v[202:205], v186 offset:39936
	global_load_lds_dwordx4 v[252:253], off
	s_waitcnt lgkmcnt(8)
	s_barrier
	s_waitcnt lgkmcnt(0)
	s_setprio 1
	v_mfma_f32_16x16x32_bf16 v[116:119], v[134:137], v[164:167], v[116:119]
	v_mfma_f32_16x16x32_bf16 v[112:115], v[142:145], v[164:167], v[112:115]
	v_mfma_f32_16x16x32_bf16 v[108:111], v[134:137], v[172:175], v[108:111]
	v_mfma_f32_16x16x32_bf16 v[104:107], v[142:145], v[172:175], v[104:107]
	v_mfma_f32_16x16x32_bf16 v[92:95], v[134:137], v[190:193], v[92:95]
	v_mfma_f32_16x16x32_bf16 v[88:91], v[142:145], v[190:193], v[88:91]
	v_mfma_f32_16x16x32_bf16 v[76:79], v[134:137], v[198:201], v[76:79]
	v_mfma_f32_16x16x32_bf16 v[72:75], v[142:145], v[198:201], v[72:75]
	v_mfma_f32_16x16x32_bf16 v[116:119], v[138:141], v[168:171], v[116:119]
	v_mfma_f32_16x16x32_bf16 v[112:115], v[146:149], v[168:171], v[112:115]
	v_mfma_f32_16x16x32_bf16 v[108:111], v[138:141], v[176:179], v[108:111]
	v_mfma_f32_16x16x32_bf16 v[104:107], v[146:149], v[176:179], v[104:107]
	v_mfma_f32_16x16x32_bf16 v[92:95], v[138:141], v[194:197], v[92:95]
	v_mfma_f32_16x16x32_bf16 v[88:91], v[146:149], v[194:197], v[88:91]
	v_lshl_add_u64 v[246:247], v[150:151], 0, s[10:11]
	v_mfma_f32_16x16x32_bf16 v[76:79], v[138:141], v[202:205], v[76:79]
	v_lshl_add_u64 v[248:249], v[180:181], 0, s[10:11]
	v_mfma_f32_16x16x32_bf16 v[72:75], v[146:149], v[202:205], v[72:75]
	s_setprio 0
	s_barrier
	s_mov_b32 m0, s54
	ds_read_b128 v[206:209], v133
	ds_read_b128 v[210:213], v133 offset:1024
	ds_read_b128 v[214:217], v133 offset:2048
	global_load_lds_dwordx4 v[246:247], off
	s_mov_b32 m0, s55
	ds_read_b128 v[222:225], v133 offset:3072
	global_load_lds_dwordx4 v[248:249], off
	s_barrier
	s_waitcnt lgkmcnt(0)
	s_setprio 1
	v_mfma_f32_16x16x32_bf16 v[124:127], v[206:209], v[164:167], v[124:127]
	v_mfma_f32_16x16x32_bf16 v[120:123], v[214:217], v[164:167], v[120:123]
	v_mfma_f32_16x16x32_bf16 v[100:103], v[206:209], v[172:175], v[100:103]
	v_mfma_f32_16x16x32_bf16 v[96:99], v[214:217], v[172:175], v[96:99]
	v_mfma_f32_16x16x32_bf16 v[84:87], v[206:209], v[190:193], v[84:87]
	v_mfma_f32_16x16x32_bf16 v[80:83], v[214:217], v[190:193], v[80:83]
	v_mfma_f32_16x16x32_bf16 v[68:71], v[206:209], v[198:201], v[68:71]
	v_mfma_f32_16x16x32_bf16 v[64:67], v[214:217], v[198:201], v[64:67]
	v_mfma_f32_16x16x32_bf16 v[124:127], v[210:213], v[168:171], v[124:127]
	v_mfma_f32_16x16x32_bf16 v[120:123], v[222:225], v[168:171], v[120:123]
	v_mfma_f32_16x16x32_bf16 v[100:103], v[210:213], v[176:179], v[100:103]
	v_mfma_f32_16x16x32_bf16 v[96:99], v[222:225], v[176:179], v[96:99]
	v_mfma_f32_16x16x32_bf16 v[84:87], v[210:213], v[194:197], v[84:87]
	v_mfma_f32_16x16x32_bf16 v[80:83], v[222:225], v[194:197], v[80:83]
	v_lshl_add_u64 v[250:251], v[218:219], 0, s[10:11]
	v_mfma_f32_16x16x32_bf16 v[68:71], v[210:213], v[202:205], v[68:71]
	v_lshl_add_u64 v[252:253], v[226:227], 0, s[10:11]
	v_mfma_f32_16x16x32_bf16 v[64:67], v[222:225], v[202:205], v[64:67]
	s_setprio 0
	s_mov_b32 m0, s42
	s_barrier
	ds_read_b128 v[164:167], v186 offset:49152
	ds_read_b128 v[168:171], v186 offset:50176
	ds_read_b128 v[172:175], v186 offset:51200
	ds_read_b128 v[176:179], v186 offset:52224
	ds_read_b128 v[190:193], v186 offset:53248
	ds_read_b128 v[194:197], v186 offset:54272
	ds_read_b128 v[198:201], v186 offset:55296
	global_load_lds_dwordx4 v[250:251], off
	s_mov_b32 m0, s43
	ds_read_b128 v[202:205], v186 offset:56320
	global_load_lds_dwordx4 v[252:253], off
	s_barrier
;     ...
;         G_PAIR(0, 1);
; #pragma unroll 1
;         for (int t = 2; t < nt; t += 2) G_PAIR(t, 0);
	s_waitcnt lgkmcnt(0)
	s_setprio 1
	v_mfma_f32_16x16x32_bf16 v[52:55], v[134:137], v[164:167], v[52:55]
	v_mfma_f32_16x16x32_bf16 v[48:51], v[142:145], v[164:167], v[48:51]
	v_mfma_f32_16x16x32_bf16 v[44:47], v[134:137], v[172:175], v[44:47]
	v_mfma_f32_16x16x32_bf16 v[36:39], v[142:145], v[172:175], v[36:39]
	v_mfma_f32_16x16x32_bf16 v[28:31], v[134:137], v[190:193], v[28:31]
	v_mfma_f32_16x16x32_bf16 v[20:23], v[142:145], v[190:193], v[20:23]
	v_mfma_f32_16x16x32_bf16 v[12:15], v[134:137], v[198:201], v[12:15]
	v_mfma_f32_16x16x32_bf16 v[4:7], v[142:145], v[198:201], v[4:7]
	v_mfma_f32_16x16x32_bf16 v[52:55], v[138:141], v[168:171], v[52:55]
	v_mfma_f32_16x16x32_bf16 v[48:51], v[146:149], v[168:171], v[48:51]
	v_mfma_f32_16x16x32_bf16 v[44:47], v[138:141], v[176:179], v[44:47]
	v_mfma_f32_16x16x32_bf16 v[36:39], v[146:149], v[176:179], v[36:39]
	s_add_u32 s26, s26, 0xb0080
	v_mfma_f32_16x16x32_bf16 v[28:31], v[138:141], v[194:197], v[28:31]
	s_addc_u32 s27, s27, 0
	v_mfma_f32_16x16x32_bf16 v[20:23], v[146:149], v[194:197], v[20:23]
	v_lshl_add_u64 v[246:247], s[26:27], 0, v[154:155]
	v_mfma_f32_16x16x32_bf16 v[12:15], v[138:141], v[202:205], v[12:15]
	v_lshl_add_u64 v[248:249], s[26:27], 0, v[158:159]
	v_mfma_f32_16x16x32_bf16 v[4:7], v[146:149], v[202:205], v[4:7]
	s_setprio 0
	s_mov_b32 m0, s56
	s_barrier
	global_load_lds_dwordx4 v[246:247], off
	s_mov_b32 m0, s57
	s_nop 0
	global_load_lds_dwordx4 v[248:249], off
	s_waitcnt vmcnt(6)
	s_barrier
	s_setprio 1
	v_mfma_f32_16x16x32_bf16 v[60:63], v[206:209], v[164:167], v[60:63]
	v_mfma_f32_16x16x32_bf16 v[56:59], v[214:217], v[164:167], v[56:59]
	v_mfma_f32_16x16x32_bf16 v[40:43], v[206:209], v[172:175], v[40:43]
	v_mfma_f32_16x16x32_bf16 v[32:35], v[214:217], v[172:175], v[32:35]
	v_mfma_f32_16x16x32_bf16 v[24:27], v[206:209], v[190:193], v[24:27]
	v_mfma_f32_16x16x32_bf16 v[16:19], v[214:217], v[190:193], v[16:19]
	v_mfma_f32_16x16x32_bf16 v[8:11], v[206:209], v[198:201], v[8:11]
	v_mfma_f32_16x16x32_bf16 v[0:3], v[214:217], v[198:201], v[0:3]
	v_mfma_f32_16x16x32_bf16 v[60:63], v[210:213], v[168:171], v[60:63]
	v_mfma_f32_16x16x32_bf16 v[56:59], v[222:225], v[168:171], v[56:59]
	v_mfma_f32_16x16x32_bf16 v[40:43], v[210:213], v[176:179], v[40:43]
	v_mfma_f32_16x16x32_bf16 v[32:35], v[222:225], v[176:179], v[32:35]
	v_mfma_f32_16x16x32_bf16 v[24:27], v[210:213], v[194:197], v[24:27]
	v_mfma_f32_16x16x32_bf16 v[16:19], v[222:225], v[194:197], v[16:19]
	v_mfma_f32_16x16x32_bf16 v[8:11], v[210:213], v[202:205], v[8:11]
	v_mfma_f32_16x16x32_bf16 v[0:3], v[222:225], v[202:205], v[0:3]
	s_setprio 0
	s_add_i32 s58, s58, 2
	s_add_u32 s24, s24, 0x100
	s_addc_u32 s25, s25, 0
	s_cmp_gt_u32 s58, 41
	s_barrier
	s_cbranch_scc0 .LBB0_1906
; __device__ __forceinline__ unsigned pk2(float lo, float hi) { unsigned r; asm volatile("v_cvt_pk_bf16_f32 %0, %1, %2" : "=v"(r) : "v"(lo), "v"(hi)); return r; }
; __device__ __forceinline__ unsigned pk2(float lo, float hi) { return f2bf(lo) | (f2bf(hi) << 16); }
;     __device__ __forceinline__ void epi(const f32x4 (&acc)[2][2][4][2], const Unit& u, int wr, int wc, int fr, int fq) const {
;     ...
;         const int row0 = u.pm * 256 + wr * 64 + fr, col0 = u.pn * 256 + wc * 32 + 8 * fq;
; #pragma unroll
;         for (int ai = 0; ai < 2; ++ai) {
;             u32x4 xo[4][2];
; #pragma unroll
;             for (int m = 0; m < 4; ++m)
; #pragma unroll
;                 for (int bj = 0; bj < 2; ++bj) xo[m][bj] = *(const u32x4*)(xb + (size_t)(row0 + ai * 128 + m * 16) * D + col0 + bj * 128);
; #pragma unroll
;             for (int m = 0; m < 4; ++m) {
;                 const int row = row0 + ai * 128 + m * 16; const size_t off = (size_t)row * D + col0; float ss = 0.f;
; #pragma unroll
;                 for (int bj = 0; bj < 2; ++bj) {
;                     const u32x4 o = xo[m][bj]; const f32x4 a0v = acc[ai][bj][m][0], a1v = acc[ai][bj][m][1];
;                     const float v0 = bf_lo(o.x) + coef * a0v[0], v1 = bf_hi(o.x) + coef * a0v[1], v2 = bf_lo(o.y) + coef * a0v[2], v3 = bf_hi(o.y) + coef * a0v[3];
;                     const float v4 = bf_lo(o.z) + coef * a1v[0], v5 = bf_hi(o.z) + coef * a1v[1], v6 = bf_lo(o.w) + coef * a1v[2], v7 = bf_hi(o.w) + coef * a1v[3];
;                     u32x4 w; w.x = pk2(v0, v1); w.y = pk2(v2, v3); w.z = pk2(v4, v5); w.w = pk2(v6, v7);
;                     *(u32x4*)(xb + off + bj * 128) = w;
;                     ss += ((v0 * v0 + v1 * v1) + (v2 * v2 + v3 * v3)) + ((v4 * v4 + v5 * v5) + (v6 * v6 + v7 * v7));
;                 }
;                 ss += __shfl_xor(ss, 16); ss += __shfl_xor(ss, 32);
;                 if (fq == 0) rowss[(size_t)row * 32 + u.pn * 4 + wc] = ss;
	v_lshl_or_b32 v164, s30, 8, v184
	v_lshl_add_u32 v168, s2, 8, v182
	v_ashrrev_i32_e32 v165, 31, v164
	v_lshlrev_b64 v[198:199], 1, v[164:165]
	v_ashrrev_i32_e32 v169, 31, v168
	v_lshl_add_u64 v[166:167], s[0:1], 0, v[198:199]
	v_lshlrev_b64 v[200:201], 11, v[168:169]
	v_lshl_add_u64 v[128:129], v[166:167], 0, v[200:201]
	v_mov_b32_e32 v218, 0x40000
	v_mov_b32_e32 v219, 0
	v_lshl_add_u64 v[216:217], v[128:129], 0, v[218:219]
	v_mov_b32_e32 v218, 0x8000
	global_load_dwordx4 v[190:193], v[128:129], off
	global_load_dwordx4 v[194:197], v[128:129], off offset:256
	v_or_b32_e32 v178, 16, v168
	v_or_b32_e32 v174, 32, v168
	v_or_b32_e32 v170, 48, v168
	v_ashrrev_i32_e32 v179, 31, v178
	v_ashrrev_i32_e32 v175, 31, v174
	v_ashrrev_i32_e32 v171, 31, v170
	v_lshlrev_b64 v[180:181], 11, v[178:179]
	v_lshlrev_b64 v[176:177], 11, v[174:175]
	v_lshlrev_b64 v[172:173], 11, v[170:171]
	v_lshl_add_u64 v[128:129], v[166:167], 0, v[180:181]
	v_lshl_add_u64 v[130:131], v[166:167], 0, v[176:177]
	v_lshl_add_u64 v[202:203], v[166:167], 0, v[172:173]
	global_load_dwordx4 v[148:151], v[128:129], off
	global_load_dwordx4 v[144:147], v[128:129], off offset:256
	global_load_dwordx4 v[140:143], v[130:131], off
	global_load_dwordx4 v[136:139], v[130:131], off offset:256
	global_load_dwordx4 v[132:135], v[202:203], off
	s_nop 0
	global_load_dwordx4 v[128:131], v[202:203], off offset:256
	global_load_dwordx4 v[222:225], v[216:217], off
	global_load_dwordx4 v[226:229], v[216:217], off offset:256
	v_lshl_add_u64 v[216:217], v[216:217], 0, v[218:219]
	global_load_dwordx4 v[230:233], v[216:217], off
	global_load_dwordx4 v[234:237], v[216:217], off offset:256
	v_lshl_add_u64 v[216:217], v[216:217], 0, v[218:219]
	global_load_dwordx4 v[238:241], v[216:217], off
	global_load_dwordx4 v[242:245], v[216:217], off offset:256
	v_lshl_add_u64 v[216:217], v[216:217], 0, v[218:219]
	global_load_dwordx4 v[246:249], v[216:217], off
	global_load_dwordx4 v[250:253], v[216:217], off offset:256
	v_and_b32_e32 v202, 64, v188
	v_xor_b32_e32 v189, 16, v188
	v_add_u32_e32 v202, 64, v202
	v_cmp_lt_i32_e32 vcc, v189, v202
	s_waitcnt vmcnt(8)
	v_lshlrev_b32_e32 v203, 16, v190
	v_and_b32_e32 v190, 0xffff0000, v190
	v_lshlrev_b32_e32 v204, 16, v191
	v_and_b32_e32 v191, 0xffff0000, v191
	v_lshlrev_b32_e32 v205, 16, v192
	v_and_b32_e32 v192, 0xffff0000, v192
	v_lshlrev_b32_e32 v206, 16, v193
	v_and_b32_e32 v193, 0xffff0000, v193
	v_lshlrev_b32_e32 v207, 16, v194
	v_and_b32_e32 v194, 0xffff0000, v194
	v_lshlrev_b32_e32 v208, 16, v195
	v_and_b32_e32 v195, 0xffff0000, v195
	v_lshlrev_b32_e32 v209, 16, v196
	v_and_b32_e32 v196, 0xffff0000, v196
	v_lshlrev_b32_e32 v210, 16, v197
	v_and_b32_e32 v197, 0xffff0000, v197
	v_fmac_f32_e32 v190, 0.5, v117
	v_fmac_f32_e32 v191, 0.5, v119
	v_fmac_f32_e32 v192, 0.5, v113
	v_fmac_f32_e32 v193, 0.5, v115
	v_fmac_f32_e32 v194, 0.5, v125
	v_fmac_f32_e32 v195, 0.5, v127
	v_fmac_f32_e32 v196, 0.5, v121
	v_fmac_f32_e32 v197, 0.5, v123
	v_fmac_f32_e32 v203, 0.5, v116
	v_fmac_f32_e32 v204, 0.5, v118
	v_fmac_f32_e32 v205, 0.5, v112
	v_fmac_f32_e32 v206, 0.5, v114
	v_fmac_f32_e32 v207, 0.5, v124
	v_fmac_f32_e32 v208, 0.5, v126
	v_fmac_f32_e32 v209, 0.5, v120
	v_fmac_f32_e32 v210, 0.5, v122
	v_mul_f32_e32 v112, v190, v190
	v_mul_f32_e32 v113, v191, v191
	v_mul_f32_e32 v118, v192, v192
	v_mul_f32_e32 v119, v193, v193
	v_mul_f32_e32 v120, v194, v194
	v_mul_f32_e32 v121, v195, v195
	v_mul_f32_e32 v122, v196, v196
	v_mul_f32_e32 v123, v197, v197
	v_fmac_f32_e32 v112, v203, v203
	v_fmac_f32_e32 v113, v204, v204
	v_fmac_f32_e32 v118, v205, v205
	v_fmac_f32_e32 v119, v206, v206
	v_fmac_f32_e32 v120, v207, v207
	v_fmac_f32_e32 v121, v208, v208
	v_fmac_f32_e32 v122, v209, v209
	v_fmac_f32_e32 v123, v210, v210
	v_add_f32_e32 v112, v112, v113
	v_add_f32_e32 v113, v118, v119
	v_add_f32_e32 v118, v120, v121
	v_add_f32_e32 v119, v122, v123
	v_cndmask_b32_e32 v189, v188, v189, vcc
	v_add_f32_e32 v112, v112, v113
	v_add_f32_e32 v113, v118, v119
	v_add_f32_e32 v113, v112, v113
	v_lshlrev_b32_e32 v112, 2, v189
	ds_bpermute_b32 v122, v112, v113
	v_lshl_add_u64 v[118:119], s[0:1], 0, v[200:201]
	v_cvt_pk_bf16_f32 v114, v203, v190
	v_lshl_add_u64 v[120:121], v[118:119], 0, v[198:199]
	v_cvt_pk_bf16_f32 v115, v204, v191
	v_cvt_pk_bf16_f32 v116, v205, v192
	v_cvt_pk_bf16_f32 v117, v206, v193
	global_store_dwordx4 v[120:121], v[114:117], off
	s_waitcnt lgkmcnt(0)
	s_nop 0
	v_add_f32_e32 v114, v113, v122
	v_xor_b32_e32 v113, 32, v188
	v_cmp_lt_i32_e32 vcc, v113, v202
	v_cvt_pk_bf16_f32 v116, v207, v194
	v_cvt_pk_bf16_f32 v117, v208, v195
	v_cvt_pk_bf16_f32 v118, v209, v196
	v_cvt_pk_bf16_f32 v119, v210, v197
	global_store_dwordx4 v[120:121], v[116:119], off offset:256
	s_nop 0
	v_cndmask_b32_e32 v113, v188, v113, vcc
	v_lshlrev_b32_e32 v113, 2, v113
	ds_bpermute_b32 v115, v113, v114
	s_and_saveexec_b64 s[20:21], s[4:5]
	s_cbranch_execz .LBB0_1909
	s_waitcnt lgkmcnt(0)
	v_add_f32_e32 v116, v114, v115
	s_lshl_b32 s22, s30, 2
	v_lshlrev_b64 v[114:115], 7, v[168:169]
	s_ashr_i32 s23, s22, 31
	v_lshl_add_u64 v[114:115], s[8:9], 0, v[114:115]
	v_lshl_add_u64 v[114:115], s[22:23], 2, v[114:115]
	s_lshl_b32 s2, s41, 2
	v_lshl_add_u64 v[114:115], v[114:115], 0, s[2:3]
	global_store_dword v[114:115], v116, off
